# v26 + 64-byte alignment (.p2align 6) of the six GEMM k-loop latches and the four attention loop heads (code placement)
# speedup vs baseline: 1.0181x; 1.0123x over previous
.LBB0_107:
	s_load_dwordx4 s[40:43], s[0:1], 0xe8
	v_mov_b32_e32 v201, v206
	s_lshl_b32 s62, s44, 8
	s_load_dwordx2 s[64:65], s[20:21], 0x0
	s_mul_i32 s49, s45, 0x1600
	s_mul_hi_i32 s48, s45, 0x1600
	v_ashrrev_i32_e32 v40, 3, v201
	s_waitcnt lgkmcnt(0)
	s_add_u32 s20, s42, s49
	v_lshlrev_b32_e32 v0, 4, v201
	v_mul_lo_u32 v2, v40, s93
	s_movk_i32 s5, 0x70
	s_addc_u32 s21, s43, s48
	s_ashr_i32 s63, s62, 31
	s_mul_i32 s61, s44, 0x160000
	v_and_or_b32 v0, v0, s5, v2
	s_mul_hi_i32 s72, s62, 0x1600
	s_add_u32 s40, s50, s61
	v_add_u32_e32 v34, 0x58000, v0
	v_add_u32_e32 v36, 0xb0000, v0
	s_addc_u32 s41, s51, s72
	global_load_dwordx4 v[2:5], v0, s[20:21]
	global_load_dwordx4 v[6:9], v0, s[40:41]
	global_load_dwordx4 v[10:13], v34, s[20:21]
	global_load_dwordx4 v[14:17], v34, s[40:41]
	global_load_dwordx4 v[18:21], v36, s[20:21]
	global_load_dwordx4 v[22:25], v36, s[40:41]
	v_add_u32_e32 v38, 0x108000, v0
	global_load_dwordx4 v[26:29], v38, s[20:21]
	global_load_dwordx4 v[30:33], v38, s[40:41]
	global_load_dwordx4 v[144:147], v0, s[20:21] offset:128
	global_load_dwordx4 v[148:151], v0, s[40:41] offset:128
	global_load_dwordx4 v[152:155], v34, s[20:21] offset:128
	global_load_dwordx4 v[156:159], v34, s[40:41] offset:128
	global_load_dwordx4 v[160:163], v36, s[20:21] offset:128
	global_load_dwordx4 v[164:167], v36, s[40:41] offset:128
	global_load_dwordx4 v[168:171], v38, s[20:21] offset:128
	global_load_dwordx4 v[172:175], v38, s[40:41] offset:128
	v_lshlrev_b32_e32 v48, 7, v40
	v_lshrrev_b32_e32 v40, 1, v40
	s_movk_i32 s4, 0x100
	v_xor_b32_e32 v40, v40, v201
	s_add_u32 s20, s89, s61
	v_mov_b32_e32 v35, v1
	v_mov_b32_e32 v37, v1
	v_mov_b32_e32 v39, v1
	v_cmp_gt_u32_e64 s[44:45], s4, v201
	v_lshlrev_b32_e32 v40, 4, v40
	s_addc_u32 s21, s90, s72
	v_readlane_b32 s4, v254, 35
	v_lshlrev_b32_e32 v42, 7, v201
	v_bfe_u32 v43, v201, 1, 3
	v_lshrrev_b32_e32 v229, 5, v201
	v_bfe_u32 v204, v201, 5, 1
	v_and_or_b32 v198, v40, s5, v48
	v_lshl_add_u64 v[176:177], s[20:21], 0, v[38:39]
	v_lshl_add_u64 v[178:179], s[20:21], 0, v[36:37]
	v_lshl_add_u64 v[180:181], s[20:21], 0, v[34:35]
	v_lshl_add_u64 v[182:183], s[20:21], 0, v[0:1]
	s_add_u32 s20, s4, s49
	v_readlane_b32 s4, v254, 36
	v_ashrrev_i32_e32 v41, 8, v201
	v_and_b32_e32 v44, 0xf80, v42
	v_and_b32_e32 v42, 0x6f80, v42
	v_bitop3_b32 v45, v229, v43, 1 bitop3:0x6c
	v_bitop3_b32 v46, v204, v43, 2 bitop3:0x36
	v_bitop3_b32 v47, v204, v43, 4 bitop3:0x36
	v_bitop3_b32 v43, v204, v43, 6 bitop3:0x36
	s_addc_u32 s21, s4, s48
	v_cmp_eq_u32_e64 s[42:43], 1, v41
	v_cmp_ne_u32_e64 s[46:47], 1, v41
	v_lshl_or_b32 v192, v41, 14, v44
	v_or_b32_e32 v193, 0x8000, v42
	v_lshlrev_b32_e32 v194, 4, v45
	v_lshlrev_b32_e32 v195, 4, v46
	v_lshlrev_b32_e32 v196, 4, v47
	v_lshlrev_b32_e32 v197, 4, v43
	v_lshl_add_u64 v[184:185], s[20:21], 0, v[38:39]
	v_lshl_add_u64 v[186:187], s[20:21], 0, v[36:37]
	v_lshl_add_u64 v[188:189], s[20:21], 0, v[34:35]
	v_lshl_add_u64 v[190:191], s[20:21], 0, v[0:1]
	v_mov_b32_e32 v0, v1
	v_cmp_lt_u32_e32 vcc, s76, v201
	s_mov_b64 s[20:21], 0
	s_mov_b32 s61, 0
	s_mov_b32 s72, 0
	s_waitcnt vmcnt(15)
	ds_write_b128 v198, v[2:5]
	s_waitcnt vmcnt(14)
	ds_write_b128 v198, v[6:9] offset:32768
	s_waitcnt vmcnt(13)
	ds_write_b128 v198, v[10:13] offset:8192
	s_waitcnt vmcnt(12)
	ds_write_b128 v198, v[14:17] offset:40960
	s_waitcnt vmcnt(11)
	ds_write_b128 v198, v[18:21] offset:16384
	s_waitcnt vmcnt(10)
	ds_write_b128 v198, v[22:25] offset:49152
	s_waitcnt vmcnt(9)
	ds_write_b128 v198, v[26:29] offset:24576
	s_waitcnt vmcnt(8)
	ds_write_b128 v198, v[30:33] offset:57344
	v_mov_b32_e32 v14, v1
	v_mov_b32_e32 v15, v1
	v_mov_b32_e32 v2, v1
	v_mov_b32_e32 v3, v1
	v_mov_b32_e32 v4, v1
	v_mov_b32_e32 v5, v1
	v_mov_b32_e32 v6, v1
	v_mov_b32_e32 v7, v1
	v_mov_b32_e32 v8, v1
	v_mov_b32_e32 v9, v1
	v_mov_b32_e32 v10, v1
	v_mov_b32_e32 v11, v1
	v_mov_b32_e32 v12, v1
	v_mov_b32_e32 v13, v1
	v_mov_b64_e32 v[30:31], v[14:15]
	v_mov_b64_e32 v[46:47], v[14:15]
	v_mov_b64_e32 v[62:63], v[14:15]
	v_mov_b64_e32 v[78:79], v[14:15]
	v_mov_b64_e32 v[94:95], v[14:15]
	v_mov_b64_e32 v[110:111], v[14:15]
	v_mov_b64_e32 v[126:127], v[14:15]
	v_mov_b64_e32 v[142:143], v[14:15]
	v_mov_b64_e32 v[28:29], v[12:13]
	v_mov_b64_e32 v[26:27], v[10:11]
	v_mov_b64_e32 v[24:25], v[8:9]
	v_mov_b64_e32 v[22:23], v[6:7]
	v_mov_b64_e32 v[20:21], v[4:5]
	v_mov_b64_e32 v[18:19], v[2:3]
	v_mov_b64_e32 v[16:17], v[0:1]
	v_mov_b64_e32 v[44:45], v[12:13]
	v_mov_b64_e32 v[42:43], v[10:11]
	v_mov_b64_e32 v[40:41], v[8:9]
	v_mov_b64_e32 v[38:39], v[6:7]
	v_mov_b64_e32 v[36:37], v[4:5]
	v_mov_b64_e32 v[34:35], v[2:3]
	v_mov_b64_e32 v[32:33], v[0:1]
	v_mov_b64_e32 v[60:61], v[12:13]
	v_mov_b64_e32 v[58:59], v[10:11]
	v_mov_b64_e32 v[56:57], v[8:9]
	v_mov_b64_e32 v[54:55], v[6:7]
	v_mov_b64_e32 v[52:53], v[4:5]
	v_mov_b64_e32 v[50:51], v[2:3]
	v_mov_b64_e32 v[48:49], v[0:1]
	v_mov_b64_e32 v[76:77], v[12:13]
	v_mov_b64_e32 v[74:75], v[10:11]
	v_mov_b64_e32 v[72:73], v[8:9]
	v_mov_b64_e32 v[70:71], v[6:7]
	v_mov_b64_e32 v[68:69], v[4:5]
	v_mov_b64_e32 v[66:67], v[2:3]
	v_mov_b64_e32 v[64:65], v[0:1]
	v_mov_b64_e32 v[92:93], v[12:13]
	v_mov_b64_e32 v[90:91], v[10:11]
	v_mov_b64_e32 v[88:89], v[8:9]
	v_mov_b64_e32 v[86:87], v[6:7]
	v_mov_b64_e32 v[84:85], v[4:5]
	v_mov_b64_e32 v[82:83], v[2:3]
	v_mov_b64_e32 v[80:81], v[0:1]
	v_mov_b64_e32 v[108:109], v[12:13]
	v_mov_b64_e32 v[106:107], v[10:11]
	v_mov_b64_e32 v[104:105], v[8:9]
	v_mov_b64_e32 v[102:103], v[6:7]
	v_mov_b64_e32 v[100:101], v[4:5]
	v_mov_b64_e32 v[98:99], v[2:3]
	v_mov_b64_e32 v[96:97], v[0:1]
	v_mov_b64_e32 v[124:125], v[12:13]
	v_mov_b64_e32 v[122:123], v[10:11]
	v_mov_b64_e32 v[120:121], v[8:9]
	v_mov_b64_e32 v[118:119], v[6:7]
	v_mov_b64_e32 v[116:117], v[4:5]
	v_mov_b64_e32 v[114:115], v[2:3]
	v_mov_b64_e32 v[112:113], v[0:1]
	v_mov_b64_e32 v[140:141], v[12:13]
	v_mov_b64_e32 v[138:139], v[10:11]
	v_mov_b64_e32 v[136:137], v[8:9]
	v_mov_b64_e32 v[134:135], v[6:7]
	v_mov_b64_e32 v[132:133], v[4:5]
	v_mov_b64_e32 v[130:131], v[2:3]
	v_mov_b64_e32 v[128:129], v[0:1]
	s_waitcnt lgkmcnt(0)
	s_barrier
	s_branch .LBB0_109
	.p2align 6

.LBB0_337:
	s_or_b64 exec, exec, s[42:43]
	global_load_dwordx4 v[172:175], v[44:45], off offset:128
	v_lshlrev_b32_e32 v0, 7, v193
	v_and_b32_e32 v2, 0xf80, v0
	v_bfe_u32 v3, v193, 1, 3
	v_lshrrev_b32_e32 v192, 5, v193
	v_and_b32_e32 v0, 0x6f80, v0
	v_bfe_u32 v196, v193, 5, 1
	v_or_b32_e32 v199, 0x8000, v0
	v_bitop3_b32 v0, v192, v3, 1 bitop3:0x6c
	v_lshlrev_b32_e32 v201, 4, v0
	v_bitop3_b32 v0, v196, v3, 2 bitop3:0x36
	s_add_u32 s20, s20, s48
	v_ashrrev_i32_e32 v197, 8, v193
	v_lshlrev_b32_e32 v202, 4, v0
	v_bitop3_b32 v0, v196, v3, 4 bitop3:0x36
	s_addc_u32 s21, s21, s49
	v_lshl_or_b32 v198, v197, 14, v2
	v_lshlrev_b32_e32 v203, 4, v0
	v_bitop3_b32 v0, v196, v3, 6 bitop3:0x36
	v_add_u32_e32 v2, v47, v46
	s_add_u32 s20, s20, 0x100
	v_lshlrev_b32_e32 v204, 4, v0
	v_add_u32_e32 v0, 0x60000, v2
	s_addc_u32 s21, s21, 0
	v_add_u32_e32 v4, 0x40000, v2
	v_mov_b32_e32 v5, v1
	v_add_u32_e32 v6, 0x20000, v2
	v_mov_b32_e32 v7, v1
	v_mov_b32_e32 v3, v1
	v_lshl_add_u64 v[176:177], s[20:21], 0, v[0:1]
	v_lshl_add_u64 v[178:179], s[20:21], 0, v[4:5]
	v_lshl_add_u64 v[180:181], s[20:21], 0, v[6:7]
	v_lshl_add_u64 v[182:183], s[20:21], 0, v[2:3]
	s_mul_i32 s21, s26, 0xfe
	s_mul_i32 s20, s90, 0xfe
	s_mul_i32 s21, s21, s79
	s_sub_i32 s20, s20, s21
	s_add_i32 s20, s20, -2
	s_ashr_i32 s21, s20, 31
	s_add_u32 s20, s67, s20
	s_addc_u32 s21, s91, s21
	s_movk_i32 s4, 0x100
	s_lshl_b64 s[20:21], s[20:21], 11
	v_cmp_gt_u32_e32 vcc, s4, v193
	s_add_u32 s20, s73, s20
	v_readlane_b32 s4, v254, 40
	s_addc_u32 s21, s4, s21
	v_mov_b32_e32 v14, v1
	v_mov_b32_e32 v15, v1
	v_lshl_add_u64 v[184:185], s[20:21], 0, v[0:1]
	v_lshl_add_u64 v[186:187], s[20:21], 0, v[4:5]
	v_lshl_add_u64 v[188:189], s[20:21], 0, v[6:7]
	v_lshl_add_u64 v[190:191], s[20:21], 0, v[2:3]
	v_mov_b32_e32 v0, v1
	v_mov_b32_e32 v2, v1
	v_mov_b32_e32 v4, v1
	v_mov_b32_e32 v6, v1
	v_mov_b32_e32 v8, v1
	v_mov_b32_e32 v9, v1
	v_mov_b32_e32 v10, v1
	v_mov_b32_e32 v11, v1
	v_mov_b32_e32 v12, v1
	v_mov_b32_e32 v13, v1
	v_mov_b64_e32 v[30:31], v[14:15]
	v_mov_b64_e32 v[46:47], v[14:15]
	v_mov_b64_e32 v[62:63], v[14:15]
	v_mov_b64_e32 v[78:79], v[14:15]
	v_mov_b64_e32 v[94:95], v[14:15]
	v_mov_b64_e32 v[110:111], v[14:15]
	v_mov_b64_e32 v[126:127], v[14:15]
	v_mov_b64_e32 v[142:143], v[14:15]
	v_cmp_lt_u32_e64 s[44:45], s76, v193
	v_cmp_eq_u32_e64 s[42:43], 1, v197
	v_cmp_ne_u32_e64 s[46:47], 1, v197
	s_mov_b64 s[20:21], 0
	s_mov_b32 s29, 0
	v_mov_b64_e32 v[28:29], v[12:13]
	v_mov_b64_e32 v[26:27], v[10:11]
	v_mov_b64_e32 v[24:25], v[8:9]
	v_mov_b64_e32 v[22:23], v[6:7]
	v_mov_b64_e32 v[20:21], v[4:5]
	v_mov_b64_e32 v[18:19], v[2:3]
	v_mov_b64_e32 v[16:17], v[0:1]
	v_mov_b64_e32 v[44:45], v[12:13]
	v_mov_b64_e32 v[42:43], v[10:11]
	v_mov_b64_e32 v[40:41], v[8:9]
	v_mov_b64_e32 v[38:39], v[6:7]
	v_mov_b64_e32 v[36:37], v[4:5]
	v_mov_b64_e32 v[34:35], v[2:3]
	v_mov_b64_e32 v[32:33], v[0:1]
	v_mov_b64_e32 v[60:61], v[12:13]
	v_mov_b64_e32 v[58:59], v[10:11]
	v_mov_b64_e32 v[56:57], v[8:9]
	v_mov_b64_e32 v[54:55], v[6:7]
	v_mov_b64_e32 v[52:53], v[4:5]
	v_mov_b64_e32 v[50:51], v[2:3]
	v_mov_b64_e32 v[48:49], v[0:1]
	v_mov_b64_e32 v[76:77], v[12:13]
	v_mov_b64_e32 v[74:75], v[10:11]
	v_mov_b64_e32 v[72:73], v[8:9]
	v_mov_b64_e32 v[70:71], v[6:7]
	v_mov_b64_e32 v[68:69], v[4:5]
	v_mov_b64_e32 v[66:67], v[2:3]
	v_mov_b64_e32 v[64:65], v[0:1]
	v_mov_b64_e32 v[92:93], v[12:13]
	v_mov_b64_e32 v[90:91], v[10:11]
	v_mov_b64_e32 v[88:89], v[8:9]
	v_mov_b64_e32 v[86:87], v[6:7]
	v_mov_b64_e32 v[84:85], v[4:5]
	v_mov_b64_e32 v[82:83], v[2:3]
	v_mov_b64_e32 v[80:81], v[0:1]
	v_mov_b64_e32 v[108:109], v[12:13]
	v_mov_b64_e32 v[106:107], v[10:11]
	v_mov_b64_e32 v[104:105], v[8:9]
	v_mov_b64_e32 v[102:103], v[6:7]
	v_mov_b64_e32 v[100:101], v[4:5]
	v_mov_b64_e32 v[98:99], v[2:3]
	v_mov_b64_e32 v[96:97], v[0:1]
	v_mov_b64_e32 v[124:125], v[12:13]
	v_mov_b64_e32 v[122:123], v[10:11]
	v_mov_b64_e32 v[120:121], v[8:9]
	v_mov_b64_e32 v[118:119], v[6:7]
	v_mov_b64_e32 v[116:117], v[4:5]
	v_mov_b64_e32 v[114:115], v[2:3]
	v_mov_b64_e32 v[112:113], v[0:1]
	v_mov_b64_e32 v[140:141], v[12:13]
	v_mov_b64_e32 v[138:139], v[10:11]
	v_mov_b64_e32 v[136:137], v[8:9]
	v_mov_b64_e32 v[134:135], v[6:7]
	v_mov_b64_e32 v[132:133], v[4:5]
	v_mov_b64_e32 v[130:131], v[2:3]
	v_mov_b64_e32 v[128:129], v[0:1]
	s_mov_b32 s79, 0
	s_waitcnt lgkmcnt(0)
	s_barrier
	s_branch .LBB0_339
	.p2align 6

.LBB0_477:
	s_load_dwordx16 s[4:19], s[0:1], 0xa8
	s_lshl_b32 s88, s21, 8
	s_ashr_i32 s21, s20, 31
	v_mov_b32_e32 v201, v206
	s_lshl_b64 s[20:21], s[20:21], 11
	s_waitcnt lgkmcnt(0)
	s_add_u32 s40, s16, s20
	v_ashrrev_i32_e32 v3, 3, v201
	v_lshlrev_b32_e32 v0, 4, v201
	v_lshlrev_b32_e32 v2, 11, v3
	s_movk_i32 s5, 0x70
	s_addc_u32 s41, s17, s21
	v_and_or_b32 v0, v0, s5, v2
	global_load_dwordx4 v[4:7], v0, s[40:41]
	v_add_u32_e32 v36, 0x20000, v0
	global_load_dwordx4 v[8:11], v36, s[40:41]
	v_add_u32_e32 v38, 0x40000, v0
	global_load_dwordx4 v[12:15], v38, s[40:41]
	s_ashr_i32 s89, s88, 31
	s_lshl_b64 s[48:49], s[88:89], 11
	s_add_u32 s42, s46, s48
	v_add_u32_e32 v40, 0x60000, v0
	s_addc_u32 s43, s47, s49
	global_load_dwordx4 v[16:19], v40, s[40:41]
	global_load_dwordx4 v[20:23], v0, s[42:43]
	global_load_dwordx4 v[24:27], v36, s[42:43]
	global_load_dwordx4 v[28:31], v38, s[42:43]
	global_load_dwordx4 v[32:35], v40, s[42:43]
	global_load_dwordx4 v[144:147], v0, s[40:41] offset:128
	global_load_dwordx4 v[148:151], v36, s[40:41] offset:128
	global_load_dwordx4 v[156:159], v38, s[40:41] offset:128
	global_load_dwordx4 v[168:171], v40, s[40:41] offset:128
	global_load_dwordx4 v[152:155], v0, s[42:43] offset:128
	global_load_dwordx4 v[160:163], v36, s[42:43] offset:128
	global_load_dwordx4 v[164:167], v38, s[42:43] offset:128
	global_load_dwordx4 v[172:175], v40, s[42:43] offset:128
	v_lshlrev_b32_e32 v49, 7, v3
	v_lshrrev_b32_e32 v3, 1, v3
	s_movk_i32 s4, 0x100
	v_xor_b32_e32 v3, v3, v201
	s_add_u32 s48, s91, s48
	v_cmp_gt_u32_e64 s[42:43], s4, v201
	v_lshlrev_b32_e32 v3, 4, v3
	s_addc_u32 s49, s80, s49
	v_readlane_b32 s4, v254, 41
	v_lshlrev_b32_e32 v43, 7, v201
	v_bfe_u32 v44, v201, 1, 3
	v_lshrrev_b32_e32 v229, 5, v201
	v_bfe_u32 v204, v201, 5, 1
	v_and_or_b32 v198, v3, s5, v49
	s_add_u32 s20, s4, s20
	v_readlane_b32 s4, v254, 42
	v_mov_b32_e32 v37, v1
	v_mov_b32_e32 v39, v1
	v_mov_b32_e32 v41, v1
	v_ashrrev_i32_e32 v42, 8, v201
	v_and_b32_e32 v45, 0xf80, v43
	v_and_b32_e32 v43, 0x6f80, v43
	v_bitop3_b32 v46, v229, v44, 1 bitop3:0x6c
	v_bitop3_b32 v47, v204, v44, 2 bitop3:0x36
	v_bitop3_b32 v48, v204, v44, 4 bitop3:0x36
	v_bitop3_b32 v44, v204, v44, 6 bitop3:0x36
	s_addc_u32 s21, s4, s21
	v_mov_b32_e32 v2, v1
	v_cmp_eq_u32_e64 s[40:41], 1, v42
	v_cmp_ne_u32_e64 s[44:45], 1, v42
	v_lshl_or_b32 v192, v42, 14, v45
	v_or_b32_e32 v193, 0x8000, v43
	v_lshlrev_b32_e32 v194, 4, v46
	v_lshlrev_b32_e32 v195, 4, v47
	v_lshlrev_b32_e32 v196, 4, v48
	v_lshlrev_b32_e32 v197, 4, v44
	v_lshl_add_u64 v[176:177], s[48:49], 0, v[40:41]
	v_lshl_add_u64 v[178:179], s[48:49], 0, v[38:39]
	v_lshl_add_u64 v[180:181], s[48:49], 0, v[36:37]
	v_lshl_add_u64 v[182:183], s[48:49], 0, v[0:1]
	v_lshl_add_u64 v[184:185], s[20:21], 0, v[40:41]
	v_lshl_add_u64 v[186:187], s[20:21], 0, v[38:39]
	v_lshl_add_u64 v[188:189], s[20:21], 0, v[36:37]
	v_lshl_add_u64 v[190:191], s[20:21], 0, v[0:1]
	v_mov_b32_e32 v0, v1
	v_mov_b32_e32 v3, v1
	v_cmp_lt_u32_e32 vcc, s73, v201
	s_mov_b64 s[20:21], 0
	s_mov_b32 s65, 0
	s_mov_b32 s72, 0
	s_waitcnt vmcnt(15)
	ds_write_b128 v198, v[4:7]
	s_waitcnt vmcnt(14)
	ds_write_b128 v198, v[8:11] offset:8192
	s_waitcnt vmcnt(13)
	ds_write_b128 v198, v[12:15] offset:16384
	s_waitcnt vmcnt(12)
	ds_write_b128 v198, v[16:19] offset:24576
	s_waitcnt vmcnt(11)
	ds_write_b128 v198, v[20:23] offset:32768
	s_waitcnt vmcnt(10)
	ds_write_b128 v198, v[24:27] offset:40960
	s_waitcnt vmcnt(9)
	ds_write_b128 v198, v[28:31] offset:49152
	s_waitcnt vmcnt(8)
	ds_write_b128 v198, v[32:35] offset:57344
	v_mov_b32_e32 v14, v1
	v_mov_b32_e32 v15, v1
	v_mov_b32_e32 v4, v1
	v_mov_b32_e32 v5, v1
	v_mov_b32_e32 v6, v1
	v_mov_b32_e32 v7, v1
	v_mov_b32_e32 v8, v1
	v_mov_b32_e32 v9, v1
	v_mov_b32_e32 v10, v1
	v_mov_b32_e32 v11, v1
	v_mov_b32_e32 v12, v1
	v_mov_b32_e32 v13, v1
	v_mov_b64_e32 v[30:31], v[14:15]
	v_mov_b64_e32 v[46:47], v[14:15]
	v_mov_b64_e32 v[62:63], v[14:15]
	v_mov_b64_e32 v[78:79], v[14:15]
	v_mov_b64_e32 v[94:95], v[14:15]
	v_mov_b64_e32 v[110:111], v[14:15]
	v_mov_b64_e32 v[126:127], v[14:15]
	v_mov_b64_e32 v[142:143], v[14:15]
	v_mov_b64_e32 v[28:29], v[12:13]
	v_mov_b64_e32 v[26:27], v[10:11]
	v_mov_b64_e32 v[24:25], v[8:9]
	v_mov_b64_e32 v[22:23], v[6:7]
	v_mov_b64_e32 v[20:21], v[4:5]
	v_mov_b64_e32 v[18:19], v[2:3]
	v_mov_b64_e32 v[16:17], v[0:1]
	v_mov_b64_e32 v[44:45], v[12:13]
	v_mov_b64_e32 v[42:43], v[10:11]
	v_mov_b64_e32 v[40:41], v[8:9]
	v_mov_b64_e32 v[38:39], v[6:7]
	v_mov_b64_e32 v[36:37], v[4:5]
	v_mov_b64_e32 v[34:35], v[2:3]
	v_mov_b64_e32 v[32:33], v[0:1]
	v_mov_b64_e32 v[60:61], v[12:13]
	v_mov_b64_e32 v[58:59], v[10:11]
	v_mov_b64_e32 v[56:57], v[8:9]
	v_mov_b64_e32 v[54:55], v[6:7]
	v_mov_b64_e32 v[52:53], v[4:5]
	v_mov_b64_e32 v[50:51], v[2:3]
	v_mov_b64_e32 v[48:49], v[0:1]
	v_mov_b64_e32 v[76:77], v[12:13]
	v_mov_b64_e32 v[74:75], v[10:11]
	v_mov_b64_e32 v[72:73], v[8:9]
	v_mov_b64_e32 v[70:71], v[6:7]
	v_mov_b64_e32 v[68:69], v[4:5]
	v_mov_b64_e32 v[66:67], v[2:3]
	v_mov_b64_e32 v[64:65], v[0:1]
	v_mov_b64_e32 v[92:93], v[12:13]
	v_mov_b64_e32 v[90:91], v[10:11]
	v_mov_b64_e32 v[88:89], v[8:9]
	v_mov_b64_e32 v[86:87], v[6:7]
	v_mov_b64_e32 v[84:85], v[4:5]
	v_mov_b64_e32 v[82:83], v[2:3]
	v_mov_b64_e32 v[80:81], v[0:1]
	v_mov_b64_e32 v[108:109], v[12:13]
	v_mov_b64_e32 v[106:107], v[10:11]
	v_mov_b64_e32 v[104:105], v[8:9]
	v_mov_b64_e32 v[102:103], v[6:7]
	v_mov_b64_e32 v[100:101], v[4:5]
	v_mov_b64_e32 v[98:99], v[2:3]
	v_mov_b64_e32 v[96:97], v[0:1]
	v_mov_b64_e32 v[124:125], v[12:13]
	v_mov_b64_e32 v[122:123], v[10:11]
	v_mov_b64_e32 v[120:121], v[8:9]
	v_mov_b64_e32 v[118:119], v[6:7]
	v_mov_b64_e32 v[116:117], v[4:5]
	v_mov_b64_e32 v[114:115], v[2:3]
	v_mov_b64_e32 v[112:113], v[0:1]
	v_mov_b64_e32 v[140:141], v[12:13]
	v_mov_b64_e32 v[138:139], v[10:11]
	v_mov_b64_e32 v[136:137], v[8:9]
	v_mov_b64_e32 v[134:135], v[6:7]
	v_mov_b64_e32 v[132:133], v[4:5]
	v_mov_b64_e32 v[130:131], v[2:3]
	v_mov_b64_e32 v[128:129], v[0:1]
	s_waitcnt lgkmcnt(0)
	s_barrier
	s_branch .LBB0_479
	.p2align 6

.LBB0_543:
	s_and_b32 s26, s42, 7
	v_mov_b32_e32 v146, v206
	s_mulk_i32 s26, 0x900
	v_bfe_u32 v148, v146, 6, 2
	s_lshl_b32 s20, s23, 7
	s_load_dwordx16 s[4:19], s[0:1], 0xa8
	v_and_b32_e32 v12, 31, v146
	s_add_i32 s40, s20, s26
	v_lshlrev_b32_e32 v0, 5, v148
	v_or3_b32 v134, v0, s40, v12
	v_ashrrev_i32_e32 v149, 8, v146
	s_lshl_b32 s28, s22, 7
	v_ashrrev_i32_e32 v135, 31, v134
	v_lshl_add_u32 v2, v149, 6, s28
	v_lshlrev_b64 v[4:5], 12, v[134:135]
	v_bfe_u32 v145, v146, 5, 1
	s_waitcnt lgkmcnt(0)
	v_lshl_add_u64 v[4:5], s[12:13], 0, v[4:5]
	v_ashrrev_i32_e32 v3, 31, v2
	v_lshl_add_u64 v[2:3], v[2:3], 1, v[4:5]
	v_lshlrev_b32_e32 v0, 4, v145
	v_lshl_add_u64 v[2:3], v[2:3], 0, v[0:1]
	global_load_dwordx4 v[98:101], v[2:3], off
	global_load_dwordx4 v[102:105], v[2:3], off offset:32
	global_load_dwordx4 v[106:109], v[2:3], off offset:64
	global_load_dwordx4 v[110:113], v[2:3], off offset:96
	v_and_b32_e32 v2, 3, v146
	v_lshlrev_b32_e32 v3, 1, v146
	v_and_or_b32 v13, v3, 8, v2
	v_ashrrev_i32_e32 v2, 31, v146
	v_lshrrev_b32_e32 v2, 28, v2
	v_add_u32_e32 v18, v146, v2
	s_ashr_i32 s29, s28, 31
	v_ashrrev_i32_e32 v150, 4, v18
	s_lshl_b64 s[20:21], s[28:29], 1
	v_add_u32_e32 v2, s26, v150
	v_lshlrev_b32_e32 v4, 7, v150
	v_lshlrev_b32_e32 v5, 3, v146
	s_add_u32 s20, s12, s20
	v_ashrrev_i32_e32 v3, 31, v2
	v_sub_u32_e32 v4, v5, v4
	s_addc_u32 s21, s13, s21
	v_lshlrev_b64 v[2:3], 12, v[2:3]
	v_ashrrev_i32_e32 v5, 31, v4
	v_lshl_add_u64 v[2:3], s[20:21], 0, v[2:3]
	v_lshlrev_b64 v[4:5], 1, v[4:5]
	v_lshl_add_u64 v[2:3], v[2:3], 0, v[4:5]
	v_add_u32_e32 v19, 0x200, v146
	global_load_dwordx4 v[114:117], v[2:3], off offset:2048
	v_ashrrev_i32_e32 v2, 31, v19
	v_lshrrev_b32_e32 v2, 28, v2
	v_add_u32_e32 v20, v19, v2
	v_ashrrev_i32_e32 v151, 4, v20
	v_add_u32_e32 v2, s26, v151
	v_lshlrev_b32_e32 v6, 7, v151
	v_lshlrev_b32_e32 v7, 3, v19
	v_ashrrev_i32_e32 v3, 31, v2
	v_sub_u32_e32 v6, v7, v6
	s_mul_i32 s22, s22, 0x480000
	v_lshlrev_b64 v[2:3], 12, v[2:3]
	v_ashrrev_i32_e32 v7, 31, v6
	s_mul_hi_i32 s27, s28, 0x9000
	s_add_u32 s30, s14, s22
	v_lshl_add_u64 v[2:3], s[20:21], 0, v[2:3]
	v_lshlrev_b64 v[6:7], 1, v[6:7]
	s_addc_u32 s31, s15, s27
	v_lshl_add_u64 v[2:3], v[2:3], 0, v[6:7]
	s_lshl_b32 s22, s26, 1
	global_load_dwordx4 v[118:121], v[2:3], off offset:2048
	v_ashrrev_i32_e32 v21, 3, v146
	v_mov_b64_e32 v[2:3], s[30:31]
	s_mov_b32 s4, 0x9000
	s_cmp_lt_i32 s23, 2
	v_mad_i64_i32 v[8:9], s[30:31], v21, s4, v[2:3]
	s_mov_b32 s23, s52
	v_lshlrev_b32_e32 v10, 4, v146
	v_lshl_add_u64 v[8:9], v[8:9], 0, s[22:23]
	v_and_b32_e32 v10, 0x70, v10
	v_mov_b32_e32 v11, v1
	v_lshl_add_u64 v[136:137], v[8:9], 0, v[10:11]
	v_ashrrev_i32_e32 v8, 3, v19
	v_mad_i64_i32 v[2:3], s[30:31], v8, s4, v[2:3]
	v_lshl_add_u64 v[2:3], v[2:3], 0, s[22:23]
	v_lshl_add_u64 v[138:139], v[2:3], 0, v[10:11]
	global_load_dwordx4 v[122:125], v[136:137], off
	global_load_dwordx4 v[126:129], v[138:139], off
	v_and_b32_e32 v2, 0xffffff0, v18
	v_sub_u32_e32 v2, v146, v2
	v_lshlrev_b32_e32 v3, 8, v150
	v_bitop3_b32 v2, v2, v150, 15 bitop3:0x78
	v_lshl_add_u32 v152, v2, 4, v3
	v_and_b32_e32 v2, 0xffffff0, v20
	v_sub_u32_e32 v2, v19, v2
	v_lshlrev_b32_e32 v3, 8, v151
	v_bitop3_b32 v2, v2, v151, 15 bitop3:0x78
	v_lshl_add_u32 v153, v2, 4, v3
	v_lshrrev_b32_e32 v3, 1, v21
	v_xor_b32_e32 v3, v3, v146
	v_lshlrev_b32_e32 v2, 7, v21
	v_lshlrev_b32_e32 v3, 4, v3
	s_movk_i32 s4, 0x70
	v_and_or_b32 v154, v3, s4, v2
	v_lshrrev_b32_e32 v3, 1, v8
	v_xor_b32_e32 v3, v3, v146
	v_lshrrev_b32_e32 v14, 1, v146
	v_lshlrev_b32_e32 v2, 7, v8
	v_lshlrev_b32_e32 v3, 4, v3
	v_and_b32_e32 v15, 4, v14
	v_and_or_b32 v155, v3, s4, v2
	v_lshl_add_u64 v[140:141], s[20:21], 0, v[4:5]
	v_lshl_or_b32 v2, v149, 3, v145
	v_mov_b32_e32 v4, 0x6000
	v_or_b32_e32 v16, v13, v15
	v_lshl_or_b32 v157, v12, 7, v4
	v_bitop3_b32 v4, v13, v2, v15 bitop3:0x36
	v_lshlrev_b32_e32 v158, 4, v4
	v_bitop3_b32 v4, v2, v16, 2 bitop3:0x36
	v_lshlrev_b32_e32 v159, 4, v4
	v_bitop3_b32 v4, v2, v16, 4 bitop3:0x36
	v_bitop3_b32 v2, v2, v16, 6 bitop3:0x36
	v_bfe_u32 v3, v146, 1, 3
	v_lshlrev_b32_e32 v161, 4, v2
	v_bitop3_b32 v2, v145, v14, 7 bitop3:0x78
	v_lshlrev_b32_e32 v162, 4, v2
	v_bitop3_b32 v2, v145, v3, 2 bitop3:0x36
	v_lshlrev_b32_e32 v163, 4, v2
	v_bitop3_b32 v2, v145, v3, 4 bitop3:0x36
	v_and_or_b32 v17, v146, 16, v16
	v_lshlrev_b32_e32 v164, 4, v2
	v_bitop3_b32 v2, v145, v3, 6 bitop3:0x36
	v_mov_b32_e32 v50, v1
	v_mov_b32_e32 v51, v1
	v_lshl_add_u64 v[142:143], s[20:21], 0, v[6:7]
	v_lshlrev_b32_e32 v156, 8, v17
	v_lshlrev_b32_e32 v160, 4, v4
	v_lshlrev_b32_e32 v165, 4, v2
	v_mov_b32_e32 v52, v1
	v_mov_b32_e32 v53, v1
	v_mov_b32_e32 v54, v1
	v_mov_b32_e32 v55, v1
	v_mov_b32_e32 v56, v1
	v_mov_b32_e32 v57, v1
	v_mov_b32_e32 v58, v1
	v_mov_b32_e32 v59, v1
	v_mov_b32_e32 v60, v1
	v_mov_b32_e32 v61, v1
	v_mov_b32_e32 v62, v1
	v_mov_b32_e32 v63, v1
	v_mov_b32_e32 v64, v1
	v_mov_b32_e32 v65, v1
	v_mov_b64_e32 v[34:35], v[50:51]
	v_mov_b64_e32 v[18:19], v[50:51]
	v_mov_b64_e32 v[2:3], v[50:51]
	v_and_b32_e32 v147, 63, v146
	s_cselect_b32 s27, 4, 36
	s_cselect_b32 s22, -3, 1
	s_mov_b32 s30, 0
	v_mov_b32_e32 v166, 0
	v_mov_b32_e32 v130, 0xf149f2ca
	v_mov_b64_e32 v[36:37], v[52:53]
	v_mov_b64_e32 v[38:39], v[54:55]
	v_mov_b64_e32 v[40:41], v[56:57]
	v_mov_b64_e32 v[42:43], v[58:59]
	v_mov_b64_e32 v[44:45], v[60:61]
	v_mov_b64_e32 v[46:47], v[62:63]
	v_mov_b64_e32 v[48:49], v[64:65]
	v_mov_b64_e32 v[20:21], v[52:53]
	v_mov_b64_e32 v[22:23], v[54:55]
	v_mov_b64_e32 v[24:25], v[56:57]
	v_mov_b64_e32 v[26:27], v[58:59]
	v_mov_b64_e32 v[28:29], v[60:61]
	v_mov_b64_e32 v[30:31], v[62:63]
	v_mov_b64_e32 v[32:33], v[64:65]
	v_mov_b64_e32 v[4:5], v[52:53]
	v_mov_b64_e32 v[6:7], v[54:55]
	v_mov_b64_e32 v[8:9], v[56:57]
	v_mov_b64_e32 v[10:11], v[58:59]
	v_mov_b64_e32 v[12:13], v[60:61]
	v_mov_b64_e32 v[14:15], v[62:63]
	v_mov_b64_e32 v[16:17], v[64:65]
	s_waitcnt vmcnt(3)
	ds_write_b128 v152, v[114:117]
	s_waitcnt vmcnt(2)
	ds_write_b128 v153, v[118:121]
	s_waitcnt vmcnt(1)
	ds_write_b128 v154, v[122:125] offset:24576
	s_waitcnt vmcnt(0)
	ds_write_b128 v155, v[126:129] offset:24576
	s_waitcnt lgkmcnt(0)
	s_barrier
	.p2align 6

.LBB0_574:
	s_mov_b32 s20, 27
	s_abs_i32 s21, s20
	v_cvt_f32_u32_e32 v0, s21
	s_sub_i32 s23, 0, s21
	s_ashr_i32 s22, s20, 31
	v_mov_b32_e32 v193, v206
	v_rcp_iflag_f32_e32 v0, v0
	v_mov_b32_e32 v35, v1
	v_mov_b32_e32 v37, v1
	v_mov_b32_e32 v39, v1
	v_mul_f32_e32 v0, 0x4f7ffffe, v0
	v_cvt_u32_f32_e32 v0, v0
	s_nop 0
	v_readfirstlane_b32 s28, v0
	s_mul_i32 s23, s23, s28
	s_mul_hi_u32 s23, s28, s23
	s_add_i32 s28, s28, s23
	s_mul_hi_u32 s23, s27, s28
	s_mul_i32 s28, s23, s21
	s_sub_i32 s28, s27, s28
	s_add_i32 s29, s23, 1
	s_sub_i32 s30, s28, s21
	s_cmp_ge_u32 s28, s21
	s_cselect_b32 s23, s29, s23
	s_cselect_b32 s28, s30, s28
	s_add_i32 s29, s23, 1
	s_cmp_ge_u32 s28, s21
	s_cselect_b32 s21, s29, s23
	s_xor_b32 s21, s21, s22
	s_sub_i32 s21, s21, s22
	s_mul_i32 s22, s21, -9
	s_add_i32 s22, s22, 9
	s_min_i32 s22, s22, 9
	s_abs_i32 s23, s22
	v_cvt_f32_u32_e32 v0, s23
	s_sub_i32 s30, 0, s23
	s_mul_i32 s46, s21, s20
	s_sub_i32 s20, s27, s46
	v_rcp_iflag_f32_e32 v0, v0
	s_abs_i32 s28, s20
	s_xor_b32 s29, s20, s22
	s_ashr_i32 s29, s29, 31
	v_mul_f32_e32 v0, 0x4f7ffffe, v0
	v_cvt_u32_f32_e32 v0, v0
	s_load_dwordx16 s[4:19], s[0:1], 0xa8
	s_waitcnt lgkmcnt(0)
	s_load_dwordx2 s[4:5], s[0:1], 0x170
	v_readfirstlane_b32 s31, v0
	s_mul_i32 s30, s30, s31
	s_mul_hi_u32 s30, s31, s30
	s_add_i32 s31, s31, s30
	s_mul_hi_u32 s30, s28, s31
	s_mul_i32 s31, s30, s23
	s_sub_i32 s28, s28, s31
	s_add_i32 s40, s30, 1
	s_sub_i32 s31, s28, s23
	s_cmp_ge_u32 s28, s23
	s_cselect_b32 s30, s40, s30
	s_cselect_b32 s28, s31, s28
	s_add_i32 s31, s30, 1
	s_cmp_ge_u32 s28, s23
	s_cselect_b32 s23, s31, s30
	v_readlane_b32 s28, v254, 8
	s_add_i32 s21, s21, s28
	s_xor_b32 s23, s23, s29
	s_mul_i32 s47, s21, 9
	s_sub_i32 s21, s23, s29
	s_add_i32 s20, s47, s20
	s_mul_i32 s48, s21, s22
	s_sub_i32 s20, s20, s48
	s_lshl_b32 s28, s20, 8
	s_ashr_i32 s29, s28, 31
	s_lshl_b32 s22, s21, 8
	s_lshl_b64 s[20:21], s[28:29], 11
	s_add_u32 s30, s10, s20
	v_lshlrev_b32_e32 v0, 4, v193
	s_addc_u32 s31, s11, s21
	s_ashr_i32 s23, s22, 31
	v_ashrrev_i32_e32 v40, 3, v193
	v_and_b32_e32 v0, 0x70, v0
	s_lshl_b64 s[20:21], s[22:23], 11
	v_lshl_or_b32 v0, v40, 11, v0
	s_waitcnt lgkmcnt(0)
	s_add_u32 s40, s4, s20
	v_add_u32_e32 v34, 0x20000, v0
	v_add_u32_e32 v36, 0x40000, v0
	v_add_u32_e32 v38, 0x60000, v0
	s_addc_u32 s41, s5, s21
	global_load_dwordx4 v[2:5], v0, s[30:31]
	global_load_dwordx4 v[6:9], v34, s[30:31]
	global_load_dwordx4 v[10:13], v36, s[30:31]
	global_load_dwordx4 v[14:17], v38, s[30:31]
	global_load_dwordx4 v[18:21], v0, s[40:41]
	global_load_dwordx4 v[22:25], v34, s[40:41]
	global_load_dwordx4 v[26:29], v36, s[40:41]
	global_load_dwordx4 v[30:33], v38, s[40:41]
	global_load_dwordx4 v[144:147], v0, s[30:31] offset:128
	global_load_dwordx4 v[148:151], v34, s[30:31] offset:128
	global_load_dwordx4 v[156:159], v36, s[30:31] offset:128
	global_load_dwordx4 v[168:171], v38, s[30:31] offset:128
	global_load_dwordx4 v[152:155], v0, s[40:41] offset:128
	global_load_dwordx4 v[160:163], v34, s[40:41] offset:128
	global_load_dwordx4 v[164:167], v36, s[40:41] offset:128
	global_load_dwordx4 v[172:175], v38, s[40:41] offset:128
	v_lshlrev_b32_e32 v48, 7, v40
	v_lshrrev_b32_e32 v40, 1, v40
	s_movk_i32 s4, 0x100
	v_xor_b32_e32 v40, v40, v193
	v_cmp_gt_u32_e64 s[40:41], s4, v193
	v_lshlrev_b32_e32 v40, 4, v40
	s_movk_i32 s4, 0x70
	v_and_or_b32 v201, v40, s4, v48
	v_readlane_b32 s4, v254, 48
	s_add_u32 s20, s4, s20
	v_readlane_b32 s4, v254, 49
	s_addc_u32 s21, s4, s21
	s_add_i32 s27, s27, s47
	v_lshl_add_u64 v[176:177], s[20:21], 0, v[38:39]
	v_lshl_add_u64 v[178:179], s[20:21], 0, v[36:37]
	v_lshl_add_u64 v[180:181], s[20:21], 0, v[34:35]
	v_lshl_add_u64 v[182:183], s[20:21], 0, v[0:1]
	s_sub_i32 s20, s27, s46
	s_sub_i32 s20, s20, s48
	s_lshl_b32 s20, s20, 8
	s_ashr_i32 s21, s20, 31
	s_lshl_b64 s[20:21], s[20:21], 11
	v_readlane_b32 s4, v254, 50
	v_lshlrev_b32_e32 v42, 7, v193
	v_bfe_u32 v43, v193, 1, 3
	v_lshrrev_b32_e32 v192, 5, v193
	v_bfe_u32 v194, v193, 5, 1
	s_add_u32 s20, s4, s20
	v_readlane_b32 s4, v254, 51
	v_ashrrev_i32_e32 v41, 8, v193
	v_and_b32_e32 v44, 0xf80, v42
	v_and_b32_e32 v42, 0x6f80, v42
	v_bitop3_b32 v45, v192, v43, 1 bitop3:0x6c
	v_bitop3_b32 v46, v194, v43, 2 bitop3:0x36
	v_bitop3_b32 v47, v194, v43, 4 bitop3:0x36
	v_bitop3_b32 v43, v194, v43, 6 bitop3:0x36
	s_addc_u32 s21, s4, s21
	v_cmp_eq_u32_e32 vcc, 1, v41
	v_cmp_ne_u32_e64 s[44:45], 1, v41
	v_lshl_or_b32 v195, v41, 14, v44
	v_or_b32_e32 v196, 0x8000, v42
	v_lshlrev_b32_e32 v197, 4, v45
	v_lshlrev_b32_e32 v198, 4, v46
	v_lshlrev_b32_e32 v199, 4, v47
	v_lshlrev_b32_e32 v200, 4, v43
	v_lshl_add_u64 v[184:185], s[20:21], 0, v[38:39]
	v_lshl_add_u64 v[186:187], s[20:21], 0, v[36:37]
	v_lshl_add_u64 v[188:189], s[20:21], 0, v[34:35]
	v_lshl_add_u64 v[190:191], s[20:21], 0, v[0:1]
	v_mov_b32_e32 v0, v1
	v_cmp_lt_u32_e64 s[42:43], s66, v193
	s_mov_b64 s[20:21], 0
	s_mov_b32 s27, 0
	s_mov_b32 s29, 0
	s_waitcnt vmcnt(15)
	ds_write_b128 v201, v[2:5]
	s_waitcnt vmcnt(14)
	ds_write_b128 v201, v[6:9] offset:8192
	s_waitcnt vmcnt(13)
	ds_write_b128 v201, v[10:13] offset:16384
	s_waitcnt vmcnt(12)
	ds_write_b128 v201, v[14:17] offset:24576
	s_waitcnt vmcnt(11)
	ds_write_b128 v201, v[18:21] offset:32768
	s_waitcnt vmcnt(10)
	ds_write_b128 v201, v[22:25] offset:40960
	s_waitcnt vmcnt(9)
	ds_write_b128 v201, v[26:29] offset:49152
	s_waitcnt vmcnt(8)
	ds_write_b128 v201, v[30:33] offset:57344
	v_mov_b32_e32 v14, v1
	v_mov_b32_e32 v15, v1
	v_mov_b32_e32 v2, v1
	v_mov_b32_e32 v3, v1
	v_mov_b32_e32 v4, v1
	v_mov_b32_e32 v5, v1
	v_mov_b32_e32 v6, v1
	v_mov_b32_e32 v7, v1
	v_mov_b32_e32 v8, v1
	v_mov_b32_e32 v9, v1
	v_mov_b32_e32 v10, v1
	v_mov_b32_e32 v11, v1
	v_mov_b32_e32 v12, v1
	v_mov_b32_e32 v13, v1
	v_mov_b64_e32 v[30:31], v[14:15]
	v_mov_b64_e32 v[46:47], v[14:15]
	v_mov_b64_e32 v[62:63], v[14:15]
	v_mov_b64_e32 v[78:79], v[14:15]
	v_mov_b64_e32 v[94:95], v[14:15]
	v_mov_b64_e32 v[110:111], v[14:15]
	v_mov_b64_e32 v[126:127], v[14:15]
	v_mov_b64_e32 v[142:143], v[14:15]
	v_mov_b64_e32 v[28:29], v[12:13]
	v_mov_b64_e32 v[26:27], v[10:11]
	v_mov_b64_e32 v[24:25], v[8:9]
	v_mov_b64_e32 v[22:23], v[6:7]
	v_mov_b64_e32 v[20:21], v[4:5]
	v_mov_b64_e32 v[18:19], v[2:3]
	v_mov_b64_e32 v[16:17], v[0:1]
	v_mov_b64_e32 v[44:45], v[12:13]
	v_mov_b64_e32 v[42:43], v[10:11]
	v_mov_b64_e32 v[40:41], v[8:9]
	v_mov_b64_e32 v[38:39], v[6:7]
	v_mov_b64_e32 v[36:37], v[4:5]
	v_mov_b64_e32 v[34:35], v[2:3]
	v_mov_b64_e32 v[32:33], v[0:1]
	v_mov_b64_e32 v[60:61], v[12:13]
	v_mov_b64_e32 v[58:59], v[10:11]
	v_mov_b64_e32 v[56:57], v[8:9]
	v_mov_b64_e32 v[54:55], v[6:7]
	v_mov_b64_e32 v[52:53], v[4:5]
	v_mov_b64_e32 v[50:51], v[2:3]
	v_mov_b64_e32 v[48:49], v[0:1]
	v_mov_b64_e32 v[76:77], v[12:13]
	v_mov_b64_e32 v[74:75], v[10:11]
	v_mov_b64_e32 v[72:73], v[8:9]
	v_mov_b64_e32 v[70:71], v[6:7]
	v_mov_b64_e32 v[68:69], v[4:5]
	v_mov_b64_e32 v[66:67], v[2:3]
	v_mov_b64_e32 v[64:65], v[0:1]
	v_mov_b64_e32 v[92:93], v[12:13]
	v_mov_b64_e32 v[90:91], v[10:11]
	v_mov_b64_e32 v[88:89], v[8:9]
	v_mov_b64_e32 v[86:87], v[6:7]
	v_mov_b64_e32 v[84:85], v[4:5]
	v_mov_b64_e32 v[82:83], v[2:3]
	v_mov_b64_e32 v[80:81], v[0:1]
	v_mov_b64_e32 v[108:109], v[12:13]
	v_mov_b64_e32 v[106:107], v[10:11]
	v_mov_b64_e32 v[104:105], v[8:9]
	v_mov_b64_e32 v[102:103], v[6:7]
	v_mov_b64_e32 v[100:101], v[4:5]
	v_mov_b64_e32 v[98:99], v[2:3]
	v_mov_b64_e32 v[96:97], v[0:1]
	v_mov_b64_e32 v[124:125], v[12:13]
	v_mov_b64_e32 v[122:123], v[10:11]
	v_mov_b64_e32 v[120:121], v[8:9]
	v_mov_b64_e32 v[118:119], v[6:7]
	v_mov_b64_e32 v[116:117], v[4:5]
	v_mov_b64_e32 v[114:115], v[2:3]
	v_mov_b64_e32 v[112:113], v[0:1]
	v_mov_b64_e32 v[140:141], v[12:13]
	v_mov_b64_e32 v[138:139], v[10:11]
	v_mov_b64_e32 v[136:137], v[8:9]
	v_mov_b64_e32 v[134:135], v[6:7]
	v_mov_b64_e32 v[132:133], v[4:5]
	v_mov_b64_e32 v[130:131], v[2:3]
	v_mov_b64_e32 v[128:129], v[0:1]
	s_waitcnt lgkmcnt(0)
	s_barrier
	s_branch .LBB0_576
	.p2align 6

.LBB0_596:
	s_cmp_gt_u32 s31, 53
	s_cselect_b64 s[20:21], -1, 0
	s_cmpk_lt_u32 s31, 0x5a
	s_cselect_b32 s26, 1, 2
	s_and_b64 s[22:23], s[20:21], exec
	s_cselect_b32 s48, s26, 0
	s_sub_i32 s22, s31, 54
	s_cmp_lt_u32 s22, 36
	s_cselect_b64 s[22:23], -1, 0
	s_and_b64 s[26:27], s[22:23], exec
	s_movk_i32 s26, 0xffca
	s_cselect_b32 s28, s26, 0xffffffa6
	s_and_b64 s[26:27], s[20:21], exec
	s_mov_b32 s26, 9
	s_cselect_b32 s27, s28, 0
	s_abs_i32 s28, s26
	v_cvt_f32_u32_e32 v0, s28
	s_sub_i32 s42, 0, s28
	s_add_i32 s29, s27, s31
	s_abs_i32 s41, s29
	v_rcp_iflag_f32_e32 v0, v0
	s_xor_b32 s40, s29, s26
	s_ashr_i32 s40, s40, 31
	v_readlane_b32 s4, v254, 46
	v_mul_f32_e32 v0, 0x4f7ffffe, v0
	v_cvt_u32_f32_e32 v0, v0
	s_movk_i32 s45, 0x100
	v_mov_b32_e32 v193, v206
	v_mov_b32_e32 v35, v1
	v_readfirstlane_b32 s43, v0
	s_mul_i32 s42, s42, s43
	s_mul_hi_u32 s42, s43, s42
	s_add_i32 s43, s43, s42
	s_mul_hi_u32 s42, s41, s43
	s_mul_i32 s43, s42, s28
	s_sub_i32 s41, s41, s43
	s_add_i32 s43, s42, 1
	s_sub_i32 s44, s41, s28
	s_cmp_ge_u32 s41, s28
	s_cselect_b32 s42, s43, s42
	s_cselect_b32 s41, s44, s41
	s_add_i32 s43, s42, 1
	s_cmp_ge_u32 s41, s28
	s_cselect_b32 s28, s43, s42
	s_xor_b32 s28, s28, s40
	s_sub_i32 s40, s28, s40
	s_mul_i32 s28, s40, s26
	s_sub_i32 s26, s4, s28
	s_load_dwordx16 s[4:19], s[0:1], 0xa8
	s_add_i32 s29, s26, s29
	s_lshl_b32 s50, s29, 8
	s_lshl_b32 s46, s40, 8
	s_and_b64 s[40:41], s[20:21], exec
	s_cselect_b32 s26, s45, 0x180
	s_ashr_i32 s51, s50, 31
	s_mul_i32 s29, s29, 0x60000
	s_mul_hi_i32 s40, s50, 0x600
	s_waitcnt lgkmcnt(0)
	s_add_u32 s42, s18, s29
	s_addc_u32 s43, s19, s40
	s_and_b64 s[40:41], s[20:21], exec
	s_cselect_b32 s29, 0x180, 0
	s_lshl_b32 s40, s29, 1
	s_add_u32 s40, s42, s40
	s_addc_u32 s41, s43, 0
	s_and_b64 s[22:23], s[22:23], exec
	s_movk_i32 s22, 0x188
	s_cselect_b32 s22, 0x180, s22
	s_and_b64 s[20:21], s[20:21], exec
	s_cselect_b32 s20, s22, 0x178
	s_add_u32 s20, s0, s20
	s_addc_u32 s21, s1, 0
	s_load_dwordx2 s[20:21], s[20:21], 0x0
	s_mul_hi_i32 s23, s46, s26
	s_mul_i32 s22, s46, s26
	s_ashr_i32 s47, s46, 31
	s_lshl_b64 s[22:23], s[22:23], 1
	s_waitcnt lgkmcnt(0)
	s_add_u32 s42, s20, s22
	s_addc_u32 s43, s21, s23
	s_cmp_eq_u32 s48, 2
	s_cselect_b64 s[20:21], -1, 0
	s_and_b64 s[20:21], s[20:21], exec
	s_cselect_b32 s22, s42, s40
	s_cselect_b32 s44, s26, 0x300
	s_cselect_b32 s20, s40, s42
	s_cselect_b32 s40, 0x300, s26
	s_cselect_b32 s23, s43, s41
	v_ashrrev_i32_e32 v48, 3, v193
	v_lshlrev_b32_e32 v0, 4, v193
	v_and_b32_e32 v2, 0x70, v0
	v_mul_lo_u32 v0, s44, v48
	v_mul_lo_u32 v3, s40, v48
	s_cselect_b32 s21, s41, s43
	v_lshl_or_b32 v0, v0, 1, v2
	v_lshl_or_b32 v34, v3, 1, v2
	s_lshl_b32 s41, s44, 7
	s_lshl_b32 s40, s40, 7
	v_add_u32_e32 v36, s41, v0
	v_add_u32_e32 v38, s40, v34
	v_add_u32_e32 v40, s41, v36
	v_add_u32_e32 v42, s40, v38
	v_add_u32_e32 v44, s41, v40
	v_add_u32_e32 v46, s40, v42
	global_load_dwordx4 v[2:5], v0, s[22:23]
	global_load_dwordx4 v[6:9], v34, s[20:21]
	global_load_dwordx4 v[10:13], v36, s[22:23]
	global_load_dwordx4 v[14:17], v38, s[20:21]
	global_load_dwordx4 v[18:21], v40, s[22:23]
	global_load_dwordx4 v[22:25], v42, s[20:21]
	global_load_dwordx4 v[26:29], v44, s[22:23]
	global_load_dwordx4 v[30:33], v46, s[20:21]
	global_load_dwordx4 v[144:147], v0, s[22:23] offset:128
	global_load_dwordx4 v[148:151], v34, s[20:21] offset:128
	global_load_dwordx4 v[152:155], v36, s[22:23] offset:128
	global_load_dwordx4 v[156:159], v38, s[20:21] offset:128
	global_load_dwordx4 v[160:163], v40, s[22:23] offset:128
	global_load_dwordx4 v[164:167], v42, s[20:21] offset:128
	global_load_dwordx4 v[168:171], v44, s[22:23] offset:128
	global_load_dwordx4 v[172:175], v46, s[20:21] offset:128
	s_lshr_b32 s54, s26, 6
	v_lshlrev_b32_e32 v56, 7, v48
	v_lshrrev_b32_e32 v48, 1, v48
	s_lshl_b32 s55, s54, 16
	v_xor_b32_e32 v48, v48, v193
	s_add_u32 s22, s22, 0x100
	v_lshlrev_b32_e32 v48, 4, v48
	s_movk_i32 s4, 0x70
	s_addc_u32 s23, s23, 0
	v_lshlrev_b32_e32 v50, 7, v193
	v_bfe_u32 v51, v193, 1, 3
	v_lshrrev_b32_e32 v192, 5, v193
	v_bfe_u32 v194, v193, 5, 1
	v_and_or_b32 v201, v48, s4, v56
	s_add_u32 s20, s20, 0x100
	v_mov_b32_e32 v37, v1
	v_mov_b32_e32 v39, v1
	v_mov_b32_e32 v41, v1
	v_mov_b32_e32 v43, v1
	v_mov_b32_e32 v45, v1
	v_mov_b32_e32 v47, v1
	v_ashrrev_i32_e32 v49, 8, v193
	v_and_b32_e32 v52, 0xf80, v50
	v_and_b32_e32 v50, 0x6f80, v50
	v_bitop3_b32 v53, v192, v51, 1 bitop3:0x6c
	v_bitop3_b32 v54, v194, v51, 2 bitop3:0x36
	v_bitop3_b32 v55, v194, v51, 4 bitop3:0x36
	v_bitop3_b32 v51, v194, v51, 6 bitop3:0x36
	s_addc_u32 s21, s21, 0
	v_lshl_or_b32 v195, v49, 14, v52
	v_or_b32_e32 v196, 0x8000, v50
	v_lshlrev_b32_e32 v197, 4, v53
	v_lshlrev_b32_e32 v198, 4, v54
	v_lshlrev_b32_e32 v199, 4, v55
	v_lshlrev_b32_e32 v200, 4, v51
	v_cmp_gt_u32_e32 vcc, s45, v193
	v_cmp_eq_u32_e64 s[40:41], 1, v49
	v_cmp_ne_u32_e64 s[44:45], 1, v49
	v_lshl_add_u64 v[176:177], s[22:23], 0, v[0:1]
	s_waitcnt vmcnt(15)
	ds_write_b128 v201, v[2:5]
	s_waitcnt vmcnt(14)
	ds_write_b128 v201, v[6:9] offset:32768
	s_waitcnt vmcnt(13)
	ds_write_b128 v201, v[10:13] offset:8192
	s_waitcnt vmcnt(12)
	ds_write_b128 v201, v[14:17] offset:40960
	s_waitcnt vmcnt(11)
	ds_write_b128 v201, v[18:21] offset:16384
	s_waitcnt vmcnt(10)
	ds_write_b128 v201, v[22:25] offset:49152
	s_waitcnt vmcnt(9)
	ds_write_b128 v201, v[26:29] offset:24576
	s_waitcnt vmcnt(8)
	ds_write_b128 v201, v[30:33] offset:57344
	v_mov_b32_e32 v14, v1
	v_mov_b32_e32 v15, v1
	v_lshl_add_u64 v[178:179], s[22:23], 0, v[36:37]
	v_lshl_add_u64 v[180:181], s[22:23], 0, v[40:41]
	v_lshl_add_u64 v[182:183], s[22:23], 0, v[44:45]
	v_lshl_add_u64 v[184:185], s[20:21], 0, v[34:35]
	v_lshl_add_u64 v[186:187], s[20:21], 0, v[38:39]
	v_lshl_add_u64 v[188:189], s[20:21], 0, v[42:43]
	v_lshl_add_u64 v[190:191], s[20:21], 0, v[46:47]
	v_mov_b32_e32 v0, v1
	v_mov_b32_e32 v2, v1
	v_mov_b32_e32 v3, v1
	v_mov_b32_e32 v4, v1
	v_mov_b32_e32 v5, v1
	v_mov_b32_e32 v6, v1
	v_mov_b32_e32 v7, v1
	v_mov_b32_e32 v8, v1
	v_mov_b32_e32 v9, v1
	v_mov_b32_e32 v10, v1
	v_mov_b32_e32 v11, v1
	v_mov_b32_e32 v12, v1
	v_mov_b32_e32 v13, v1
	v_mov_b64_e32 v[30:31], v[14:15]
	v_mov_b64_e32 v[46:47], v[14:15]
	v_mov_b64_e32 v[62:63], v[14:15]
	v_mov_b64_e32 v[78:79], v[14:15]
	v_mov_b64_e32 v[94:95], v[14:15]
	v_mov_b64_e32 v[110:111], v[14:15]
	v_mov_b64_e32 v[126:127], v[14:15]
	v_mov_b64_e32 v[142:143], v[14:15]
	s_mov_b32 s49, 2
	s_mov_b32 s53, 0
	v_cmp_lt_u32_e64 s[42:43], s66, v193
	s_mov_b64 s[20:21], 0
	v_mov_b32_e32 v202, 0
	v_mov_b64_e32 v[28:29], v[12:13]
	v_mov_b64_e32 v[26:27], v[10:11]
	v_mov_b64_e32 v[24:25], v[8:9]
	v_mov_b64_e32 v[22:23], v[6:7]
	v_mov_b64_e32 v[20:21], v[4:5]
	v_mov_b64_e32 v[18:19], v[2:3]
	v_mov_b64_e32 v[16:17], v[0:1]
	v_mov_b64_e32 v[44:45], v[12:13]
	v_mov_b64_e32 v[42:43], v[10:11]
	v_mov_b64_e32 v[40:41], v[8:9]
	v_mov_b64_e32 v[38:39], v[6:7]
	v_mov_b64_e32 v[36:37], v[4:5]
	v_mov_b64_e32 v[34:35], v[2:3]
	v_mov_b64_e32 v[32:33], v[0:1]
	v_mov_b64_e32 v[60:61], v[12:13]
	v_mov_b64_e32 v[58:59], v[10:11]
	v_mov_b64_e32 v[56:57], v[8:9]
	v_mov_b64_e32 v[54:55], v[6:7]
	v_mov_b64_e32 v[52:53], v[4:5]
	v_mov_b64_e32 v[50:51], v[2:3]
	v_mov_b64_e32 v[48:49], v[0:1]
	v_mov_b64_e32 v[76:77], v[12:13]
	v_mov_b64_e32 v[74:75], v[10:11]
	v_mov_b64_e32 v[72:73], v[8:9]
	v_mov_b64_e32 v[70:71], v[6:7]
	v_mov_b64_e32 v[68:69], v[4:5]
	v_mov_b64_e32 v[66:67], v[2:3]
	v_mov_b64_e32 v[64:65], v[0:1]
	v_mov_b64_e32 v[92:93], v[12:13]
	v_mov_b64_e32 v[90:91], v[10:11]
	v_mov_b64_e32 v[88:89], v[8:9]
	v_mov_b64_e32 v[86:87], v[6:7]
	v_mov_b64_e32 v[84:85], v[4:5]
	v_mov_b64_e32 v[82:83], v[2:3]
	v_mov_b64_e32 v[80:81], v[0:1]
	v_mov_b64_e32 v[108:109], v[12:13]
	v_mov_b64_e32 v[106:107], v[10:11]
	v_mov_b64_e32 v[104:105], v[8:9]
	v_mov_b64_e32 v[102:103], v[6:7]
	v_mov_b64_e32 v[100:101], v[4:5]
	v_mov_b64_e32 v[98:99], v[2:3]
	v_mov_b64_e32 v[96:97], v[0:1]
	v_mov_b64_e32 v[124:125], v[12:13]
	v_mov_b64_e32 v[122:123], v[10:11]
	v_mov_b64_e32 v[120:121], v[8:9]
	v_mov_b64_e32 v[118:119], v[6:7]
	v_mov_b64_e32 v[116:117], v[4:5]
	v_mov_b64_e32 v[114:115], v[2:3]
	v_mov_b64_e32 v[112:113], v[0:1]
	v_mov_b64_e32 v[140:141], v[12:13]
	v_mov_b64_e32 v[138:139], v[10:11]
	v_mov_b64_e32 v[136:137], v[8:9]
	v_mov_b64_e32 v[134:135], v[6:7]
	v_mov_b64_e32 v[132:133], v[4:5]
	v_mov_b64_e32 v[130:131], v[2:3]
	v_mov_b64_e32 v[128:129], v[0:1]
	s_waitcnt lgkmcnt(0)
	s_barrier
	s_branch .LBB0_598
	.p2align 6

.LBB0_645:
	s_ashr_i32 s20, s26, 3
	s_lshr_b32 s21, s20, 29
	s_add_i32 s21, s20, s21
	s_and_b32 s27, s26, 7
	s_ashr_i32 s23, s21, 3
	s_and_b32 s21, s21, -8
	v_mov_b32_e32 v12, v206
	s_mulk_i32 s27, 0x900
	s_sub_i32 s42, s20, s21
	s_add_i32 s40, s27, 0x100
	v_and_b32_e32 v13, 31, v12
	v_ashrrev_i32_e32 v0, 1, v12
	s_lshl_b32 s31, s42, 8
	v_and_b32_e32 v0, 0xffffffe0, v0
	v_or_b32_e32 v2, s40, v13
	s_lshl_b32 s22, s23, 7
	s_waitcnt vmcnt(20)
	v_add3_u32 v146, v2, v0, s31
	s_waitcnt lgkmcnt(0)
	v_mov_b64_e32 v[2:3], s[84:85]
	s_movk_i32 s4, 0xc00
	s_waitcnt vmcnt(17)
	v_bfe_u32 v156, v12, 5, 1
	s_lshl_b32 s20, s23, 6
	s_ashr_i32 s23, s22, 31
	v_mad_i64_i32 v[2:3], s[40:41], v146, s4, v[2:3]
	s_and_b32 s20, s20, 0xffffff80
	v_lshl_add_u64 v[2:3], s[22:23], 1, v[2:3]
	v_lshlrev_b32_e32 v0, 4, v156
	s_ashr_i32 s21, s20, 31
	v_lshl_add_u64 v[2:3], v[2:3], 0, v[0:1]
	v_ashrrev_i32_e32 v0, 31, v12
	s_mul_hi_i32 s29, s20, 0x9000
	s_mul_i32 s28, s20, 0x9000
	s_lshl_b64 s[20:21], s[20:21], 1
	v_lshrrev_b32_e32 v0, 28, v0
	s_add_u32 s20, s84, s20
	v_add_u32_e32 v14, v12, v0
	s_addc_u32 s21, s85, s21
	v_ashrrev_i32_e32 v157, 4, v14
	v_add_u32_e32 v0, s27, v157
	v_mov_b64_e32 v[4:5], s[20:21]
	v_mad_i64_i32 v[6:7], s[40:41], v0, s4, v[4:5]
	v_lshlrev_b32_e32 v0, 7, v157
	v_lshlrev_b32_e32 v8, 3, v12
	v_add_u32_e32 v15, 0x200, v12
	v_sub_u32_e32 v8, v8, v0
	v_ashrrev_i32_e32 v0, 31, v15
	v_lshrrev_b32_e32 v0, 28, v0
	v_ashrrev_i32_e32 v9, 31, v8
	v_add_u32_e32 v16, v15, v0
	v_lshlrev_b64 v[8:9], 1, v[8:9]
	v_ashrrev_i32_e32 v158, 4, v16
	v_lshl_add_u64 v[6:7], v[6:7], 0, v[8:9]
	v_add_u32_e32 v0, s27, v158
	global_load_dwordx4 v[98:101], v[6:7], off offset:2048
	v_mad_i64_i32 v[4:5], s[40:41], v0, s4, v[4:5]
	v_lshlrev_b32_e32 v0, 7, v158
	v_lshlrev_b32_e32 v6, 3, v15
	v_sub_u32_e32 v6, v6, v0
	v_ashrrev_i32_e32 v7, 31, v6
	s_add_u32 s28, s86, s28
	v_lshlrev_b64 v[6:7], 1, v[6:7]
	s_addc_u32 s29, s87, s29
	v_lshl_add_u64 v[4:5], v[4:5], 0, v[6:7]
	global_load_dwordx4 v[102:105], v[4:5], off offset:2048
	v_ashrrev_i32_e32 v17, 3, v12
	v_mov_b64_e32 v[4:5], s[28:29]
	s_mov_b32 s4, 0x9000
	s_lshl_b32 s30, s27, 1
	v_mad_i64_i32 v[10:11], s[28:29], v17, s4, v[4:5]
	s_mov_b32 s31, s52
	v_lshlrev_b32_e32 v0, 4, v12
	v_lshl_add_u64 v[10:11], v[10:11], 0, s[30:31]
	v_and_b32_e32 v0, 0x70, v0
	v_lshl_add_u64 v[148:149], v[10:11], 0, v[0:1]
	v_ashrrev_i32_e32 v10, 3, v15
	v_mad_i64_i32 v[4:5], s[28:29], v10, s4, v[4:5]
	v_lshl_add_u64 v[4:5], v[4:5], 0, s[30:31]
	v_lshl_add_u64 v[150:151], v[4:5], 0, v[0:1]
	global_load_dwordx4 v[138:141], v[148:149], off
	global_load_dwordx4 v[142:145], v[150:151], off
	global_load_dwordx4 v[106:109], v[2:3], off
	global_load_dwordx4 v[110:113], v[2:3], off offset:32
	global_load_dwordx4 v[114:117], v[2:3], off offset:64
	global_load_dwordx4 v[118:121], v[2:3], off offset:96
	global_load_dwordx4 v[122:125], v[2:3], off offset:128
	global_load_dwordx4 v[126:129], v[2:3], off offset:160
	global_load_dwordx4 v[130:133], v[2:3], off offset:192
	global_load_dwordx4 v[134:137], v[2:3], off offset:224
	v_and_b32_e32 v5, 0xffffff0, v14
	v_sub_u32_e32 v5, v12, v5
	v_lshlrev_b32_e32 v11, 8, v157
	v_bitop3_b32 v5, v5, v157, 15 bitop3:0x78
	v_lshl_add_u32 v159, v5, 4, v11
	v_and_b32_e32 v5, 0xffffff0, v16
	v_sub_u32_e32 v5, v15, v5
	v_lshlrev_b32_e32 v11, 8, v158
	v_bitop3_b32 v5, v5, v158, 15 bitop3:0x78
	s_waitcnt vmcnt(28)
	v_lshl_add_u32 v160, v5, 4, v11
	v_lshrrev_b32_e32 v11, 1, v17
	v_xor_b32_e32 v11, v11, v12
	v_lshlrev_b32_e32 v5, 7, v17
	v_lshlrev_b32_e32 v11, 4, v11
	s_movk_i32 s4, 0x70
	v_and_or_b32 v161, v11, s4, v5
	v_lshlrev_b32_e32 v5, 7, v10
	v_lshrrev_b32_e32 v10, 1, v10
	v_and_b32_e32 v2, 3, v12
	v_lshlrev_b32_e32 v3, 1, v12
	v_xor_b32_e32 v10, v10, v12
	v_and_or_b32 v2, v3, 8, v2
	v_lshrrev_b32_e32 v3, 1, v12
	v_lshlrev_b32_e32 v10, 4, v10
	v_and_b32_e32 v3, 4, v3
	v_and_or_b32 v162, v10, s4, v5
	v_mov_b32_e32 v5, 0x6000
	v_lshl_or_b32 v164, v13, 7, v5
	v_bitop3_b32 v5, v2, v156, v3 bitop3:0x36
	v_lshlrev_b32_e32 v165, 4, v5
	v_or_b32_e32 v5, 2, v156
	v_bitop3_b32 v5, v2, v5, v3 bitop3:0x36
	v_lshlrev_b32_e32 v166, 4, v5
	v_or_b32_e32 v5, 4, v156
	v_bitop3_b32 v5, v2, v5, v3 bitop3:0x36
	v_lshlrev_b32_e32 v167, 4, v5
	v_or_b32_e32 v5, 6, v156
	v_bitop3_b32 v5, v2, v5, v3 bitop3:0x36
	v_lshlrev_b32_e32 v168, 4, v5
	v_or_b32_e32 v5, 8, v156
	v_or_b32_e32 v4, v2, v3
	v_bitop3_b32 v5, v2, v5, v3 bitop3:0x36
	v_and_or_b32 v4, v12, 16, v4
	v_lshlrev_b32_e32 v169, 4, v5
	v_or_b32_e32 v5, 10, v156
	v_lshrrev_b32_e32 v0, 5, v12
	v_lshlrev_b32_e32 v163, 8, v4
	v_bfe_u32 v4, v12, 1, 3
	v_bitop3_b32 v5, v2, v5, v3 bitop3:0x36
	v_lshlrev_b32_e32 v170, 4, v5
	v_or_b32_e32 v5, 12, v156
	v_bitop3_b32 v0, v0, v4, 1 bitop3:0x6c
	v_bitop3_b32 v5, v2, v5, v3 bitop3:0x36
	v_lshlrev_b32_e32 v173, 4, v0
	v_bitop3_b32 v0, v156, v4, 2 bitop3:0x36
	v_lshlrev_b32_e32 v171, 4, v5
	v_or_b32_e32 v5, 14, v156
	v_lshlrev_b32_e32 v174, 4, v0
	v_bitop3_b32 v0, v156, v4, 4 bitop3:0x36
	v_bitop3_b32 v2, v2, v5, v3 bitop3:0x36
	v_lshlrev_b32_e32 v175, 4, v0
	v_bitop3_b32 v0, v156, v4, 6 bitop3:0x36
	v_mov_b32_e32 v14, v1
	v_mov_b32_e32 v15, v1
	v_lshl_add_u64 v[152:153], s[20:21], 0, v[8:9]
	v_lshl_add_u64 v[154:155], s[20:21], 0, v[6:7]
	v_lshlrev_b32_e32 v172, 4, v2
	v_lshlrev_b32_e32 v176, 4, v0
	v_mov_b32_e32 v0, v1
	v_mov_b32_e32 v2, v1
	v_mov_b32_e32 v3, v1
	v_mov_b32_e32 v4, v1
	v_mov_b32_e32 v5, v1
	v_mov_b32_e32 v6, v1
	v_mov_b32_e32 v7, v1
	v_mov_b32_e32 v8, v1
	v_mov_b32_e32 v9, v1
	v_mov_b32_e32 v10, v1
	v_mov_b32_e32 v11, v1
	v_mov_b32_e32 v12, v1
	v_mov_b32_e32 v13, v1
	v_mov_b64_e32 v[64:65], v[14:15]
	v_mov_b64_e32 v[48:49], v[14:15]
	v_mov_b64_e32 v[32:33], v[14:15]
	s_cmp_lt_i32 s42, 0
	v_mov_b64_e32 v[62:63], v[12:13]
	v_mov_b64_e32 v[60:61], v[10:11]
	v_mov_b64_e32 v[58:59], v[8:9]
	v_mov_b64_e32 v[56:57], v[6:7]
	v_mov_b64_e32 v[54:55], v[4:5]
	v_mov_b64_e32 v[52:53], v[2:3]
	v_mov_b64_e32 v[50:51], v[0:1]
	v_mov_b64_e32 v[46:47], v[12:13]
	v_mov_b64_e32 v[44:45], v[10:11]
	v_mov_b64_e32 v[42:43], v[8:9]
	v_mov_b64_e32 v[40:41], v[6:7]
	v_mov_b64_e32 v[38:39], v[4:5]
	v_mov_b64_e32 v[36:37], v[2:3]
	v_mov_b64_e32 v[34:35], v[0:1]
	v_mov_b64_e32 v[30:31], v[12:13]
	v_mov_b64_e32 v[28:29], v[10:11]
	v_mov_b64_e32 v[26:27], v[8:9]
	v_mov_b64_e32 v[24:25], v[6:7]
	v_mov_b64_e32 v[22:23], v[4:5]
	v_mov_b64_e32 v[20:21], v[2:3]
	v_mov_b64_e32 v[18:19], v[0:1]
	v_mov_b64_e32 v[16:17], v[14:15]
	s_mov_b32 s31, 0
	v_ashrrev_i32_e32 v147, 31, v146
	s_cselect_b32 s28, 4, 36
	s_cselect_b32 s29, -3, 1
	v_mov_b32_e32 v177, 0
	v_mov_b32_e32 v179, 0xf149f2ca
	v_mov_b64_e32 v[14:15], v[12:13]
	v_mov_b64_e32 v[12:13], v[10:11]
	v_mov_b64_e32 v[10:11], v[8:9]
	v_mov_b64_e32 v[8:9], v[6:7]
	v_mov_b64_e32 v[6:7], v[4:5]
	v_mov_b64_e32 v[4:5], v[2:3]
	v_mov_b64_e32 v[2:3], v[0:1]
	s_waitcnt vmcnt(11)
	ds_write_b128 v159, v[98:101]
	s_waitcnt vmcnt(10)
	ds_write_b128 v160, v[102:105]
	s_waitcnt vmcnt(9)
	ds_write_b128 v161, v[138:141] offset:24576
	s_waitcnt vmcnt(8)
	ds_write_b128 v162, v[142:145] offset:24576
	s_waitcnt vmcnt(0)
	s_waitcnt lgkmcnt(0)
	s_barrier
	.p2align 6

.LBB0_671:
	s_or_b64 exec, exec, s[22:23]
	s_load_dwordx16 s[4:19], s[0:1], 0xa8
	s_mul_i32 s22, s28, 0x9000
	s_mul_hi_i32 s23, s28, 0x9000
	global_load_dwordx4 v[152:155], v[24:25], off
	v_ashrrev_i32_e32 v9, 3, v4
	s_waitcnt lgkmcnt(0)
	s_add_u32 s22, s14, s22
	s_addc_u32 s23, s15, s23
	v_mov_b64_e32 v[24:25], s[22:23]
	s_mov_b32 s4, 0x9000
	s_lshl_b32 s44, s27, 1
	v_mad_i64_i32 v[26:27], s[22:23], v9, s4, v[24:25]
	s_mov_b32 s45, s52
	v_lshlrev_b32_e32 v0, 4, v4
	v_ashrrev_i32_e32 v15, 3, v18
	v_lshl_add_u64 v[26:27], v[26:27], 0, s[44:45]
	v_and_b32_e32 v0, 0x70, v0
	v_mad_i64_i32 v[18:19], s[22:23], v15, s4, v[24:25]
	v_lshl_add_u64 v[166:167], v[26:27], 0, v[0:1]
	v_lshl_add_u64 v[18:19], v[18:19], 0, s[44:45]
	v_lshl_add_u64 v[168:169], v[18:19], 0, v[0:1]
	global_load_dwordx4 v[156:159], v[166:167], off
	global_load_dwordx4 v[160:163], v[168:169], off
	v_lshlrev_b32_e32 v21, 1, v4
	v_lshrrev_b32_e32 v24, 1, v4
	s_movk_i32 s4, 0x180
	v_lshrrev_b32_e32 v26, 1, v175
	v_mov_b32_e32 v3, 0x6000
	v_and_b32_e32 v0, 3, v4
	v_mul_lo_u32 v25, v175, s4
	v_lshrrev_b32_e32 v30, 1, v183
	v_lshl_or_b32 v184, v5, 7, v3
	v_lshl_add_u64 v[18:19], v[22:23], 1, s[20:21]
	v_and_b32_e32 v5, 8, v21
	v_and_b32_e32 v21, 4, v24
	v_bitop3_b32 v8, v26, v8, 7 bitop3:0x6c
	v_lshlrev_b32_e32 v22, 7, v9
	v_lshrrev_b32_e32 v9, 1, v9
	v_lshlrev_b32_e32 v23, 7, v15
	v_lshrrev_b32_e32 v15, 1, v15
	v_lshrrev_b32_e32 v28, 1, v179
	v_mul_lo_u32 v29, v183, s4
	v_bitop3_b32 v20, v30, v20, 7 bitop3:0x6c
	v_or3_b32 v0, v5, v0, v21
	v_lshl_add_u32 v185, v8, 4, v25
	v_xor_b32_e32 v5, v9, v4
	v_xor_b32_e32 v8, v15, v4
	v_mul_lo_u32 v27, v179, s4
	v_bitop3_b32 v14, v28, v14, 7 bitop3:0x6c
	v_lshl_add_u32 v187, v20, 4, v29
	v_lshlrev_b32_e32 v5, 4, v5
	v_lshlrev_b32_e32 v8, 4, v8
	s_movk_i32 s5, 0x70
	v_lshl_add_u32 v186, v14, 4, v27
	s_waitcnt vmcnt(4)
	ds_write_b128 v185, v[144:147]
	s_waitcnt vmcnt(3)
	ds_write_b128 v186, v[148:151]
	v_and_or_b32 v191, v5, s5, v22
	v_and_or_b32 v192, v8, s5, v23
	v_lshrrev_b32_e32 v9, 1, v0
	v_bfe_u32 v31, v4, 1, 3
	v_mov_b32_e32 v3, v1
	v_mov_b32_e32 v7, v1
	v_and_or_b32 v0, v4, 16, v0
	v_xor_b32_e32 v4, v9, v171
	v_bitop3_b32 v5, v9, v171, 2 bitop3:0x1e
	v_mov_b32_e32 v14, 0x3000
	v_lshl_add_u64 v[12:13], v[12:13], 1, s[20:21]
	v_lshl_add_u64 v[16:17], v[16:17], 1, s[20:21]
	v_bitop3_b32 v24, v171, v24, 7 bitop3:0x78
	v_bitop3_b32 v26, v171, v31, 2 bitop3:0x36
	v_bitop3_b32 v28, v171, v31, 4 bitop3:0x36
	v_bitop3_b32 v30, v171, v31, 6 bitop3:0x36
	v_bitop3_b32 v8, v9, v171, 4 bitop3:0x1e
	v_bitop3_b32 v9, v9, v171, 6 bitop3:0x1e
	v_mad_u32_u24 v194, v0, s4, v14
	v_lshlrev_b32_e32 v195, 4, v4
	v_lshlrev_b32_e32 v196, 4, v5
	v_mov_b32_e32 v14, v1
	v_mov_b32_e32 v15, v1
	v_lshlrev_b32_e32 v188, 4, v24
	v_lshlrev_b32_e32 v189, 4, v26
	v_lshlrev_b32_e32 v190, 4, v28
	s_cmp_lt_i32 s30, 1
	v_mul_u32_u24_e32 v193, 0x180, v0
	v_lshlrev_b32_e32 v197, 4, v8
	v_lshlrev_b32_e32 v198, 4, v9
	v_lshlrev_b32_e32 v199, 4, v30
	v_mov_b32_e32 v0, v1
	v_mov_b32_e32 v8, v1
	v_mov_b32_e32 v9, v1
	v_ashrrev_i32_e32 v165, 31, v164
	s_cselect_b32 s20, 4, 36
	s_waitcnt vmcnt(2)
	ds_write_b128 v187, v[152:155]
	s_waitcnt vmcnt(1)
	ds_write_b128 v191, v[156:159] offset:24576
	s_waitcnt vmcnt(0)
	ds_write_b128 v192, v[160:163] offset:24576
	s_waitcnt lgkmcnt(0)
	s_barrier
	s_load_dwordx4 s[44:47], s[0:1], 0xe8
	s_cselect_b32 s21, -3, 1
	v_cndmask_b32_e64 v170, 11, 7, vcc
	s_mov_b32 s31, 0
	v_cndmask_b32_e64 v174, 11, 7, s[40:41]
	s_waitcnt lgkmcnt(0)
	v_lshl_add_u64 v[2:3], v[2:3], 1, s[44:45]
	v_lshl_add_u64 v[4:5], v[6:7], 1, s[44:45]
	v_lshl_add_u64 v[6:7], v[10:11], 1, s[44:45]
	v_cndmask_b32_e32 v173, v13, v3, vcc
	v_cndmask_b32_e32 v172, v12, v2, vcc
	v_cndmask_b32_e64 v177, v17, v5, s[40:41]
	v_cndmask_b32_e64 v176, v16, v4, s[40:41]
	v_cndmask_b32_e64 v181, v19, v7, s[42:43]
	v_cndmask_b32_e64 v180, v18, v6, s[42:43]
	v_mov_b32_e32 v2, v1
	v_mov_b32_e32 v3, v1
	v_mov_b32_e32 v4, v1
	v_mov_b32_e32 v5, v1
	v_mov_b32_e32 v6, v1
	v_mov_b32_e32 v7, v1
	v_mov_b32_e32 v10, v1
	v_mov_b32_e32 v11, v1
	v_mov_b32_e32 v12, v1
	v_mov_b32_e32 v13, v1
	v_mov_b64_e32 v[30:31], v[14:15]
	v_mov_b64_e32 v[46:47], v[14:15]
	v_mov_b64_e32 v[62:63], v[14:15]
	v_mov_b64_e32 v[78:79], v[14:15]
	v_cndmask_b32_e64 v178, 11, 7, s[42:43]
	v_mov_b32_e32 v200, 0
	v_mov_b32_e32 v203, 0xf149f2ca
	v_mov_b64_e32 v[28:29], v[12:13]
	v_mov_b64_e32 v[26:27], v[10:11]
	v_mov_b64_e32 v[24:25], v[8:9]
	v_mov_b64_e32 v[22:23], v[6:7]
	v_mov_b64_e32 v[20:21], v[4:5]
	v_mov_b64_e32 v[18:19], v[2:3]
	v_mov_b64_e32 v[16:17], v[0:1]
	v_mov_b64_e32 v[44:45], v[12:13]
	v_mov_b64_e32 v[42:43], v[10:11]
	v_mov_b64_e32 v[40:41], v[8:9]
	v_mov_b64_e32 v[38:39], v[6:7]
	v_mov_b64_e32 v[36:37], v[4:5]
	v_mov_b64_e32 v[34:35], v[2:3]
	v_mov_b64_e32 v[32:33], v[0:1]
	v_mov_b64_e32 v[60:61], v[12:13]
	v_mov_b64_e32 v[58:59], v[10:11]
	v_mov_b64_e32 v[56:57], v[8:9]
	v_mov_b64_e32 v[54:55], v[6:7]
	v_mov_b64_e32 v[52:53], v[4:5]
	v_mov_b64_e32 v[50:51], v[2:3]
	v_mov_b64_e32 v[48:49], v[0:1]
	v_mov_b64_e32 v[76:77], v[12:13]
	v_mov_b64_e32 v[74:75], v[10:11]
	v_mov_b64_e32 v[72:73], v[8:9]
	v_mov_b64_e32 v[70:71], v[6:7]
	v_mov_b64_e32 v[68:69], v[4:5]
	v_mov_b64_e32 v[66:67], v[2:3]
	v_mov_b64_e32 v[64:65], v[0:1]
	.p2align 6

.LBB0_690:
	s_load_dwordx16 s[4:19], s[0:1], 0xa8
	s_and_b32 s20, s22, 7
	s_mul_i32 s29, s20, 0x900
	v_and_b32_e32 v5, 31, v4
	s_add_i32 s40, s27, s29
	v_ashrrev_i32_e32 v0, 1, v4
	v_and_b32_e32 v6, 0xffffffe0, v0
	v_or_b32_e32 v0, s40, v5
	s_lshl_b32 s42, s28, 6
	v_add_u32_e32 v90, v0, v6
	s_waitcnt lgkmcnt(0)
	v_mov_b64_e32 v[2:3], s[12:13]
	s_movk_i32 s4, 0xa00
	v_bfe_u32 v96, v4, 5, 1
	s_lshl_b32 s20, s28, 4
	v_mad_i64_i32 v[2:3], s[40:41], v90, s4, v[2:3]
	s_ashr_i32 s43, s42, 31
	s_andn2_b32 s20, s20, 63
	v_lshl_add_u64 v[2:3], s[42:43], 1, v[2:3]
	v_lshlrev_b32_e32 v0, 4, v96
	s_ashr_i32 s21, s20, 31
	v_lshl_add_u64 v[2:3], v[2:3], 0, v[0:1]
	v_ashrrev_i32_e32 v0, 31, v4
	s_sub_i32 s26, s26, s23
	s_mul_hi_i32 s44, s20, 0x9000
	s_mul_i32 s45, s20, 0x9000
	s_lshl_b64 s[20:21], s[20:21], 1
	v_lshrrev_b32_e32 v0, 29, v0
	s_add_u32 s20, s12, s20
	v_add_u32_e32 v7, v4, v0
	s_addc_u32 s21, s13, s21
	v_ashrrev_i32_e32 v10, 3, v7
	global_load_dwordx4 v[66:69], v[2:3], off
	global_load_dwordx4 v[70:73], v[2:3], off offset:32
	global_load_dwordx4 v[74:77], v[2:3], off offset:64
	global_load_dwordx4 v[78:81], v[2:3], off offset:96
	s_add_u32 s40, s14, s45
	v_add_u32_e32 v91, s29, v10
	v_mov_b64_e32 v[2:3], s[20:21]
	s_addc_u32 s41, s15, s44
	v_mad_i64_i32 v[8:9], s[44:45], v91, s4, v[2:3]
	v_lshlrev_b32_e32 v0, 6, v10
	v_lshlrev_b32_e32 v2, 3, v4
	v_sub_u32_e32 v2, v2, v0
	v_ashrrev_i32_e32 v3, 31, v2
	v_lshl_add_u64 v[8:9], v[2:3], 1, v[8:9]
	global_load_dwordx4 v[82:85], v[8:9], off offset:2048
	v_ashrrev_i32_e32 v11, 3, v4
	v_mov_b64_e32 v[8:9], s[40:41]
	s_mov_b32 s4, 0x9000
	v_mad_i64_i32 v[8:9], s[40:41], v11, s4, v[8:9]
	s_lshl_b32 s40, s29, 1
	s_mov_b32 s41, s52
	v_lshlrev_b32_e32 v0, 4, v4
	v_lshl_add_u64 v[8:9], v[8:9], 0, s[40:41]
	v_and_b32_e32 v0, 0x70, v0
	v_lshl_add_u64 v[92:93], v[8:9], 0, v[0:1]
	global_load_dwordx4 v[86:89], v[92:93], off
	v_and_b32_e32 v0, 0xffffff8, v7
	v_sub_u32_e32 v0, v4, v0
	v_lshrrev_b32_e32 v8, 1, v10
	v_lshlrev_b32_e32 v7, 7, v10
	v_bitop3_b32 v0, v8, v0, 7 bitop3:0x6c
	v_lshl_add_u32 v97, v0, 4, v7
	v_lshrrev_b32_e32 v7, 1, v11
	v_xor_b32_e32 v7, v7, v4
	v_lshlrev_b32_e32 v0, 7, v11
	v_lshlrev_b32_e32 v7, 4, v7
	s_movk_i32 s4, 0x70
	s_movk_i32 s5, 0xa00
	v_and_or_b32 v98, v7, s4, v0
	s_cmp_lt_i32 s26, -3
	s_waitcnt vmcnt(1)
	ds_write_b128 v97, v[82:85]
	s_waitcnt vmcnt(0)
	ds_write_b128 v98, v[86:89] offset:24576
	s_waitcnt lgkmcnt(0)
	s_barrier
	s_cbranch_scc1 .LBB0_702
	v_lshl_add_u64 v[94:95], v[2:3], 1, s[20:21]
	v_lshlrev_b32_e32 v0, 1, v4
	v_lshrrev_b32_e32 v3, 1, v4
	v_and_b32_e32 v0, 8, v0
	v_and_b32_e32 v2, 3, v4
	v_and_b32_e32 v7, 4, v3
	v_or3_b32 v0, v0, v2, v7
	v_and_or_b32 v2, v4, 16, v0
	v_lshlrev_b32_e32 v99, 7, v2
	v_or_b32_e32 v2, s27, v5
	v_lshrrev_b32_e32 v0, 1, v0
	v_add_u32_e32 v101, v2, v6
	v_bfe_u32 v2, v4, 1, 3
	v_mov_b32_e32 v4, 0x6000
	v_lshl_or_b32 v102, v5, 7, v4
	v_xor_b32_e32 v4, v0, v96
	v_lshlrev_b32_e32 v103, 4, v4
	v_bitop3_b32 v4, v0, v96, 2 bitop3:0x1e
	v_lshlrev_b32_e32 v104, 4, v4
	v_bitop3_b32 v4, v0, v96, 4 bitop3:0x1e
	v_bitop3_b32 v0, v0, v96, 6 bitop3:0x1e
	v_lshlrev_b32_e32 v106, 4, v0
	v_bitop3_b32 v0, v96, v3, 7 bitop3:0x78
	v_lshlrev_b32_e32 v114, 4, v0
	v_bitop3_b32 v0, v96, v2, 2 bitop3:0x36
	v_lshlrev_b32_e32 v115, 4, v0
	v_bitop3_b32 v0, v96, v2, 4 bitop3:0x36
	v_lshlrev_b32_e32 v116, 4, v0
	v_bitop3_b32 v0, v96, v2, 6 bitop3:0x36
	v_mov_b32_e32 v14, v1
	v_mov_b32_e32 v15, v1
	v_lshlrev_b32_e32 v105, 4, v4
	v_lshlrev_b32_e32 v117, 4, v0
	v_mov_b32_e32 v0, v1
	v_mov_b32_e32 v2, v1
	v_mov_b32_e32 v3, v1
	v_mov_b32_e32 v4, v1
	v_mov_b32_e32 v5, v1
	v_mov_b32_e32 v6, v1
	v_mov_b32_e32 v7, v1
	v_mov_b32_e32 v8, v1
	v_mov_b32_e32 v9, v1
	v_mov_b32_e32 v10, v1
	v_mov_b32_e32 v11, v1
	v_mov_b32_e32 v12, v1
	v_mov_b32_e32 v13, v1
	v_mov_b64_e32 v[32:33], v[14:15]
	v_mov_b64_e32 v[30:31], v[12:13]
	v_mov_b64_e32 v[28:29], v[10:11]
	v_mov_b64_e32 v[26:27], v[8:9]
	v_mov_b64_e32 v[24:25], v[6:7]
	v_mov_b64_e32 v[22:23], v[4:5]
	v_mov_b64_e32 v[20:21], v[2:3]
	v_mov_b64_e32 v[18:19], v[0:1]
	v_mov_b64_e32 v[16:17], v[14:15]
	v_mul_i32_i24_e32 v100, -8, v96
	s_add_i32 s27, s26, 3
	v_add_u32_e32 v107, -1, v101
	v_add_u32_e32 v108, -2, v101
	v_add_u32_e32 v109, -3, v101
	s_mov_b32 s29, -4
	v_add_u32_e32 v110, -4, v101
	v_add_u32_e32 v111, -5, v101
	v_add_u32_e32 v112, -6, v101
	v_add_u32_e32 v113, -7, v101
	v_mov_b32_e32 v118, 0
	v_mov_b32_e32 v119, 0xf149f2ca
	v_mov_b64_e32 v[14:15], v[12:13]
	v_mov_b64_e32 v[12:13], v[10:11]
	v_mov_b64_e32 v[10:11], v[8:9]
	v_mov_b64_e32 v[8:9], v[6:7]
	v_mov_b64_e32 v[6:7], v[4:5]
	v_mov_b64_e32 v[4:5], v[2:3]
	v_mov_b64_e32 v[2:3], v[0:1]
	.p2align 6

.LBB0_712:
	s_cmp_lt_u32 s21, s62
	s_cselect_b64 s[26:27], -1, 0
	s_cmp_ge_u32 s21, s62
	s_cselect_b64 s[58:59], -1, 0
	s_abs_i32 s40, s20
	v_cvt_f32_u32_e32 v0, s40
	s_sub_i32 s41, s21, s62
	s_min_u32 s21, s21, s41
	s_sub_i32 s41, 0, s40
	v_rcp_iflag_f32_e32 v0, v0
	v_readlane_b32 s4, v254, 46
	s_add_i32 s42, s21, s4
	s_xor_b32 s43, s21, s20
	v_mul_f32_e32 v0, 0x4f7ffffe, v0
	v_cvt_u32_f32_e32 v0, v0
	s_abs_i32 s21, s21
	s_ashr_i32 s43, s43, 31
	s_load_dwordx16 s[4:19], s[0:1], 0xa8
	v_readfirstlane_b32 s44, v0
	s_mul_i32 s41, s41, s44
	s_mul_hi_u32 s41, s44, s41
	s_add_i32 s44, s44, s41
	s_mul_hi_u32 s41, s21, s44
	s_mul_i32 s44, s41, s40
	s_sub_i32 s21, s21, s44
	s_add_i32 s44, s41, 1
	s_sub_i32 s45, s21, s40
	s_cmp_ge_u32 s21, s40
	s_cselect_b32 s41, s44, s41
	s_cselect_b32 s21, s45, s21
	s_add_i32 s44, s41, 1
	s_cmp_ge_u32 s21, s40
	s_cselect_b32 s21, s44, s41
	s_xor_b32 s21, s21, s43
	s_sub_i32 s65, s21, s43
	s_mul_i32 s20, s65, s20
	s_sub_i32 s20, s42, s20
	s_lshl_b32 s54, s20, 8
	s_lshl_b32 s56, s65, 8
	s_and_b64 s[20:21], s[26:27], exec
	s_cselect_b32 s40, 0, s53
	s_ashr_i32 s55, s54, 31
	s_lshl_b64 s[20:21], s[54:55], 11
	s_waitcnt lgkmcnt(0)
	s_add_u32 s41, s10, s20
	s_addc_u32 s42, s11, s21
	s_add_i32 s20, s56, s40
	s_ashr_i32 s21, s20, 31
	s_lshl_b64 s[20:21], s[20:21], 11
	v_mov_b32_e32 v193, v206
	s_add_u32 s40, s46, s20
	s_addc_u32 s43, s47, s21
	v_lshlrev_b32_e32 v0, 4, v193
	v_ashrrev_i32_e32 v40, 3, v193
	v_and_b32_e32 v0, 0x70, v0
	s_and_b64 s[20:21], s[26:27], exec
	v_lshl_or_b32 v0, v40, 11, v0
	s_cselect_b32 s21, s42, s43
	s_cselect_b32 s20, s41, s40
	v_add_u32_e32 v34, 0x20000, v0
	v_add_u32_e32 v36, 0x40000, v0
	s_cselect_b32 s49, s43, s42
	s_cselect_b32 s48, s40, s41
	global_load_dwordx4 v[2:5], v0, s[20:21]
	global_load_dwordx4 v[6:9], v0, s[48:49]
	global_load_dwordx4 v[10:13], v34, s[20:21]
	global_load_dwordx4 v[14:17], v34, s[48:49]
	global_load_dwordx4 v[18:21], v36, s[20:21]
	global_load_dwordx4 v[22:25], v36, s[48:49]
	v_add_u32_e32 v38, 0x60000, v0
	global_load_dwordx4 v[26:29], v38, s[20:21]
	global_load_dwordx4 v[30:33], v38, s[48:49]
	global_load_dwordx4 v[144:147], v0, s[20:21] offset:128
	global_load_dwordx4 v[148:151], v0, s[48:49] offset:128
	global_load_dwordx4 v[152:155], v34, s[20:21] offset:128
	global_load_dwordx4 v[156:159], v34, s[48:49] offset:128
	global_load_dwordx4 v[160:163], v36, s[20:21] offset:128
	global_load_dwordx4 v[164:167], v36, s[48:49] offset:128
	global_load_dwordx4 v[168:171], v38, s[20:21] offset:128
	global_load_dwordx4 v[172:175], v38, s[48:49] offset:128
	v_lshlrev_b32_e32 v48, 7, v40
	v_lshrrev_b32_e32 v40, 1, v40
	s_movk_i32 s4, 0x100
	v_xor_b32_e32 v40, v40, v193
	s_add_u32 s48, s48, 0x100
	v_cmp_gt_u32_e32 vcc, s4, v193
	v_lshlrev_b32_e32 v40, 4, v40
	s_movk_i32 s4, 0x70
	s_addc_u32 s49, s49, 0
	v_lshlrev_b32_e32 v42, 7, v193
	v_bfe_u32 v43, v193, 1, 3
	v_lshrrev_b32_e32 v192, 5, v193
	v_bfe_u32 v194, v193, 5, 1
	v_and_or_b32 v201, v40, s4, v48
	s_add_u32 s20, s20, 0x100
	v_mov_b32_e32 v35, v1
	v_mov_b32_e32 v37, v1
	v_mov_b32_e32 v39, v1
	v_ashrrev_i32_e32 v41, 8, v193
	v_and_b32_e32 v44, 0xf80, v42
	v_and_b32_e32 v42, 0x6f80, v42
	v_bitop3_b32 v45, v192, v43, 1 bitop3:0x6c
	v_bitop3_b32 v46, v194, v43, 2 bitop3:0x36
	v_bitop3_b32 v47, v194, v43, 4 bitop3:0x36
	v_bitop3_b32 v43, v194, v43, 6 bitop3:0x36
	s_addc_u32 s21, s21, 0
	v_cmp_eq_u32_e64 s[40:41], 1, v41
	v_cmp_ne_u32_e64 s[44:45], 1, v41
	v_lshl_or_b32 v195, v41, 14, v44
	v_or_b32_e32 v196, 0x8000, v42
	v_lshlrev_b32_e32 v197, 4, v45
	v_lshlrev_b32_e32 v198, 4, v46
	v_lshlrev_b32_e32 v199, 4, v47
	v_lshlrev_b32_e32 v200, 4, v43
	v_lshl_add_u64 v[176:177], s[48:49], 0, v[38:39]
	v_lshl_add_u64 v[178:179], s[48:49], 0, v[36:37]
	v_lshl_add_u64 v[180:181], s[48:49], 0, v[34:35]
	v_lshl_add_u64 v[182:183], s[48:49], 0, v[0:1]
	v_lshl_add_u64 v[184:185], s[20:21], 0, v[38:39]
	v_lshl_add_u64 v[186:187], s[20:21], 0, v[36:37]
	v_lshl_add_u64 v[188:189], s[20:21], 0, v[34:35]
	v_lshl_add_u64 v[190:191], s[20:21], 0, v[0:1]
	v_mov_b32_e32 v0, v1
	s_mov_b32 s26, 0
	v_cmp_lt_u32_e64 s[42:43], s66, v193
	s_mov_b32 s27, 0
	s_waitcnt vmcnt(15)
	ds_write_b128 v201, v[2:5]
	s_waitcnt vmcnt(14)
	ds_write_b128 v201, v[6:9] offset:32768
	s_waitcnt vmcnt(13)
	ds_write_b128 v201, v[10:13] offset:8192
	s_waitcnt vmcnt(12)
	ds_write_b128 v201, v[14:17] offset:40960
	s_waitcnt vmcnt(11)
	ds_write_b128 v201, v[18:21] offset:16384
	s_waitcnt vmcnt(10)
	ds_write_b128 v201, v[22:25] offset:49152
	s_waitcnt vmcnt(9)
	ds_write_b128 v201, v[26:29] offset:24576
	s_waitcnt vmcnt(8)
	ds_write_b128 v201, v[30:33] offset:57344
	v_mov_b32_e32 v14, v1
	v_mov_b32_e32 v15, v1
	v_mov_b32_e32 v2, v1
	v_mov_b32_e32 v3, v1
	v_mov_b32_e32 v4, v1
	v_mov_b32_e32 v5, v1
	v_mov_b32_e32 v6, v1
	v_mov_b32_e32 v7, v1
	v_mov_b32_e32 v8, v1
	v_mov_b32_e32 v9, v1
	v_mov_b32_e32 v10, v1
	v_mov_b32_e32 v11, v1
	v_mov_b32_e32 v12, v1
	v_mov_b32_e32 v13, v1
	v_mov_b64_e32 v[30:31], v[14:15]
	v_mov_b64_e32 v[46:47], v[14:15]
	v_mov_b64_e32 v[62:63], v[14:15]
	v_mov_b64_e32 v[78:79], v[14:15]
	v_mov_b64_e32 v[94:95], v[14:15]
	v_mov_b64_e32 v[110:111], v[14:15]
	v_mov_b64_e32 v[126:127], v[14:15]
	v_mov_b64_e32 v[142:143], v[14:15]
	v_mov_b64_e32 v[28:29], v[12:13]
	v_mov_b64_e32 v[26:27], v[10:11]
	v_mov_b64_e32 v[24:25], v[8:9]
	v_mov_b64_e32 v[22:23], v[6:7]
	v_mov_b64_e32 v[20:21], v[4:5]
	v_mov_b64_e32 v[18:19], v[2:3]
	v_mov_b64_e32 v[16:17], v[0:1]
	v_mov_b64_e32 v[44:45], v[12:13]
	v_mov_b64_e32 v[42:43], v[10:11]
	v_mov_b64_e32 v[40:41], v[8:9]
	v_mov_b64_e32 v[38:39], v[6:7]
	v_mov_b64_e32 v[36:37], v[4:5]
	v_mov_b64_e32 v[34:35], v[2:3]
	v_mov_b64_e32 v[32:33], v[0:1]
	v_mov_b64_e32 v[60:61], v[12:13]
	v_mov_b64_e32 v[58:59], v[10:11]
	v_mov_b64_e32 v[56:57], v[8:9]
	v_mov_b64_e32 v[54:55], v[6:7]
	v_mov_b64_e32 v[52:53], v[4:5]
	v_mov_b64_e32 v[50:51], v[2:3]
	v_mov_b64_e32 v[48:49], v[0:1]
	v_mov_b64_e32 v[76:77], v[12:13]
	v_mov_b64_e32 v[74:75], v[10:11]
	v_mov_b64_e32 v[72:73], v[8:9]
	v_mov_b64_e32 v[70:71], v[6:7]
	v_mov_b64_e32 v[68:69], v[4:5]
	v_mov_b64_e32 v[66:67], v[2:3]
	v_mov_b64_e32 v[64:65], v[0:1]
	v_mov_b64_e32 v[92:93], v[12:13]
	v_mov_b64_e32 v[90:91], v[10:11]
	v_mov_b64_e32 v[88:89], v[8:9]
	v_mov_b64_e32 v[86:87], v[6:7]
	v_mov_b64_e32 v[84:85], v[4:5]
	v_mov_b64_e32 v[82:83], v[2:3]
	v_mov_b64_e32 v[80:81], v[0:1]
	v_mov_b64_e32 v[108:109], v[12:13]
	v_mov_b64_e32 v[106:107], v[10:11]
	v_mov_b64_e32 v[104:105], v[8:9]
	v_mov_b64_e32 v[102:103], v[6:7]
	v_mov_b64_e32 v[100:101], v[4:5]
	v_mov_b64_e32 v[98:99], v[2:3]
	v_mov_b64_e32 v[96:97], v[0:1]
	v_mov_b64_e32 v[124:125], v[12:13]
	v_mov_b64_e32 v[122:123], v[10:11]
	v_mov_b64_e32 v[120:121], v[8:9]
	v_mov_b64_e32 v[118:119], v[6:7]
	v_mov_b64_e32 v[116:117], v[4:5]
	v_mov_b64_e32 v[114:115], v[2:3]
	v_mov_b64_e32 v[112:113], v[0:1]
	v_mov_b64_e32 v[140:141], v[12:13]
	v_mov_b64_e32 v[138:139], v[10:11]
	v_mov_b64_e32 v[136:137], v[8:9]
	v_mov_b64_e32 v[134:135], v[6:7]
	v_mov_b64_e32 v[132:133], v[4:5]
	v_mov_b64_e32 v[130:131], v[2:3]
	v_mov_b64_e32 v[128:129], v[0:1]
	s_waitcnt lgkmcnt(0)
	s_barrier
	s_branch .LBB0_714
	.p2align 6
